# GEMM K-loops: dropped the no-op lgkmcnt(0) after each compute-segment barrier and the mid-segment setprio 0/1 flip (3 issue slots per 32-MFMA segment), on top of the FFN adaLN load hoist
# speedup vs baseline: 1.0188x; 1.0052x over previous
.LBB0_182:
	s_add_u32 s6, s4, 0xfffc0080
	s_addc_u32 s7, s5, -1
	s_add_i32 s9, 0, 0x10000
	s_cmp_eq_u32 s53, 12
	s_cselect_b32 s27, s39, s7
	s_cselect_b32 s26, s49, s6
	v_add_u32_e32 v0, s9, v189
	s_cselect_b32 s7, s15, s52
	s_cselect_b32 s6, s50, s51
	s_add_i32 s83, 0, 0x14000
	ds_read_b128 v[130:133], v0
	ds_read_b128 v[134:137], v0 offset:1024
	ds_read_b128 v[162:165], v0 offset:2048
	ds_read_b128 v[166:169], v0 offset:3072
	v_add_u32_e32 v0, s83, v189
	ds_read_b128 v[170:173], v0
	ds_read_b128 v[174:177], v0 offset:1024
	ds_read_b128 v[178:181], v0 offset:2048
	ds_read_b128 v[182:185], v0 offset:3072
	v_lshl_add_u64 v[148:149], s[4:5], 0, v[158:159]
	s_add_i32 m0, s40, 0xc000
	ds_read_b128 v[196:199], v193
	ds_read_b128 v[200:203], v193 offset:1024
	ds_read_b128 v[204:207], v193 offset:2048
	ds_read_b128 v[208:211], v193 offset:3072
	ds_read_b128 v[212:215], v193 offset:4096
	ds_read_b128 v[216:219], v193 offset:5120
	ds_read_b128 v[220:223], v193 offset:6144
	ds_read_b128 v[224:227], v193 offset:7168
	global_load_lds_dwordx4 v[148:149], off
	v_lshl_add_u64 v[148:149], s[4:5], 0, v[160:161]
	s_add_i32 m0, s40, 0xe000
	s_nop 0
	global_load_lds_dwordx4 v[148:149], off
	s_waitcnt vmcnt(8)
	s_waitcnt lgkmcnt(0)
	s_barrier
	s_setprio 1
	v_mfma_f32_16x16x32_bf16 v[126:129], v[130:133], v[196:199], v[126:129]
	v_mfma_f32_16x16x32_bf16 v[122:125], v[162:165], v[196:199], v[122:125]
	v_mfma_f32_16x16x32_bf16 v[118:121], v[130:133], v[204:207], v[118:121]
	v_mfma_f32_16x16x32_bf16 v[114:117], v[162:165], v[204:207], v[114:117]
	v_mfma_f32_16x16x32_bf16 v[102:105], v[130:133], v[212:215], v[102:105]
	v_mfma_f32_16x16x32_bf16 v[98:101], v[162:165], v[212:215], v[98:101]
	v_mfma_f32_16x16x32_bf16 v[86:89], v[130:133], v[220:223], v[86:89]
	v_mfma_f32_16x16x32_bf16 v[82:85], v[162:165], v[220:223], v[82:85]
	v_mfma_f32_16x16x32_bf16 v[126:129], v[134:137], v[200:203], v[126:129]
	v_mfma_f32_16x16x32_bf16 v[122:125], v[166:169], v[200:203], v[122:125]
	v_mfma_f32_16x16x32_bf16 v[118:121], v[134:137], v[208:211], v[118:121]
	v_mfma_f32_16x16x32_bf16 v[114:117], v[166:169], v[208:211], v[114:117]
	v_mfma_f32_16x16x32_bf16 v[102:105], v[134:137], v[216:219], v[102:105]
	v_mfma_f32_16x16x32_bf16 v[98:101], v[166:169], v[216:219], v[98:101]
	v_mfma_f32_16x16x32_bf16 v[86:89], v[134:137], v[224:227], v[86:89]
	v_mfma_f32_16x16x32_bf16 v[82:85], v[166:169], v[224:227], v[82:85]
	v_mfma_f32_16x16x32_bf16 v[110:113], v[170:173], v[196:199], v[110:113]
	v_mfma_f32_16x16x32_bf16 v[106:109], v[178:181], v[196:199], v[106:109]
	v_mfma_f32_16x16x32_bf16 v[94:97], v[170:173], v[204:207], v[94:97]
	v_mfma_f32_16x16x32_bf16 v[90:93], v[178:181], v[204:207], v[90:93]
	v_mfma_f32_16x16x32_bf16 v[78:81], v[170:173], v[212:215], v[78:81]
	v_mfma_f32_16x16x32_bf16 v[74:77], v[178:181], v[212:215], v[74:77]
	v_mfma_f32_16x16x32_bf16 v[70:73], v[170:173], v[220:223], v[70:73]
	v_mfma_f32_16x16x32_bf16 v[66:69], v[178:181], v[220:223], v[66:69]
	v_mfma_f32_16x16x32_bf16 v[110:113], v[174:177], v[200:203], v[110:113]
	v_mfma_f32_16x16x32_bf16 v[106:109], v[182:185], v[200:203], v[106:109]
	v_mfma_f32_16x16x32_bf16 v[94:97], v[174:177], v[208:211], v[94:97]
	v_mfma_f32_16x16x32_bf16 v[90:93], v[182:185], v[208:211], v[90:93]
	v_mfma_f32_16x16x32_bf16 v[78:81], v[174:177], v[216:219], v[78:81]
	v_mfma_f32_16x16x32_bf16 v[74:77], v[182:185], v[216:219], v[74:77]
	v_mfma_f32_16x16x32_bf16 v[70:73], v[174:177], v[224:227], v[70:73]
	v_mfma_f32_16x16x32_bf16 v[66:69], v[182:185], v[224:227], v[66:69]
	s_setprio 0
	s_barrier
	s_add_i32 s9, s9, s29
	v_lshl_add_u64 v[148:149], s[6:7], 0, v[142:143]
	s_mov_b32 m0, s9
	ds_read_b128 v[196:199], v193 offset:16384
	ds_read_b128 v[200:203], v193 offset:17408
	ds_read_b128 v[204:207], v193 offset:18432
	ds_read_b128 v[208:211], v193 offset:19456
	ds_read_b128 v[212:215], v193 offset:20480
	ds_read_b128 v[216:219], v193 offset:21504
	ds_read_b128 v[220:223], v193 offset:22528
	ds_read_b128 v[224:227], v193 offset:23552
	global_load_lds_dwordx4 v[148:149], off
	s_add_i32 m0, s9, 0x2000
	s_add_u32 s78, s6, 0x40000
	v_lshl_add_u64 v[150:151], s[6:7], 0, v[138:139]
	s_addc_u32 s79, s7, 0
	s_add_i32 s9, s83, s29
	global_load_lds_dwordx4 v[150:151], off
	v_lshl_add_u64 v[186:187], s[78:79], 0, v[142:143]
	s_mov_b32 m0, s9
	v_lshl_add_u64 v[228:229], s[26:27], 0, v[140:141]
	global_load_lds_dwordx4 v[186:187], off
	v_lshl_add_u64 v[186:187], s[78:79], 0, v[138:139]
	s_add_i32 m0, s9, 0x2000
	s_nop 0
	global_load_lds_dwordx4 v[186:187], off
	v_lshl_add_u64 v[186:187], s[26:27], 0, v[144:145]
	s_mov_b32 m0, s40
	s_nop 0
	global_load_lds_dwordx4 v[186:187], off
	s_mov_b32 m0, s41
	s_nop 0
	global_load_lds_dwordx4 v[228:229], off
	s_waitcnt vmcnt(8)
	s_waitcnt lgkmcnt(0)
	s_barrier
	s_setprio 1
	v_mfma_f32_16x16x32_bf16 v[62:65], v[130:133], v[196:199], v[62:65]
	v_mfma_f32_16x16x32_bf16 v[58:61], v[162:165], v[196:199], v[58:61]
	v_mfma_f32_16x16x32_bf16 v[54:57], v[130:133], v[204:207], v[54:57]
	v_mfma_f32_16x16x32_bf16 v[50:53], v[162:165], v[204:207], v[50:53]
	v_mfma_f32_16x16x32_bf16 v[38:41], v[130:133], v[212:215], v[38:41]
	v_mfma_f32_16x16x32_bf16 v[34:37], v[162:165], v[212:215], v[34:37]
	v_mfma_f32_16x16x32_bf16 v[22:25], v[130:133], v[220:223], v[22:25]
	v_mfma_f32_16x16x32_bf16 v[18:21], v[162:165], v[220:223], v[18:21]
	v_mfma_f32_16x16x32_bf16 v[62:65], v[134:137], v[200:203], v[62:65]
	v_mfma_f32_16x16x32_bf16 v[58:61], v[166:169], v[200:203], v[58:61]
	v_mfma_f32_16x16x32_bf16 v[54:57], v[134:137], v[208:211], v[54:57]
	v_mfma_f32_16x16x32_bf16 v[50:53], v[166:169], v[208:211], v[50:53]
	v_mfma_f32_16x16x32_bf16 v[38:41], v[134:137], v[216:219], v[38:41]
	v_mfma_f32_16x16x32_bf16 v[34:37], v[166:169], v[216:219], v[34:37]
	v_mfma_f32_16x16x32_bf16 v[22:25], v[134:137], v[224:227], v[22:25]
	v_mfma_f32_16x16x32_bf16 v[18:21], v[166:169], v[224:227], v[18:21]
	v_mfma_f32_16x16x32_bf16 v[46:49], v[170:173], v[196:199], v[46:49]
	v_mfma_f32_16x16x32_bf16 v[42:45], v[178:181], v[196:199], v[42:45]
	v_mfma_f32_16x16x32_bf16 v[30:33], v[170:173], v[204:207], v[30:33]
	v_mfma_f32_16x16x32_bf16 v[26:29], v[178:181], v[204:207], v[26:29]
	v_mfma_f32_16x16x32_bf16 v[14:17], v[170:173], v[212:215], v[14:17]
	v_mfma_f32_16x16x32_bf16 v[10:13], v[178:181], v[212:215], v[10:13]
	v_mfma_f32_16x16x32_bf16 v[6:9], v[170:173], v[220:223], v[6:9]
	v_mfma_f32_16x16x32_bf16 v[2:5], v[178:181], v[220:223], v[2:5]
	v_mfma_f32_16x16x32_bf16 v[46:49], v[174:177], v[200:203], v[46:49]
	v_mfma_f32_16x16x32_bf16 v[42:45], v[182:185], v[200:203], v[42:45]
	v_mfma_f32_16x16x32_bf16 v[30:33], v[174:177], v[208:211], v[30:33]
	v_mfma_f32_16x16x32_bf16 v[26:29], v[182:185], v[208:211], v[26:29]
	v_mfma_f32_16x16x32_bf16 v[14:17], v[174:177], v[216:219], v[14:17]
	v_mfma_f32_16x16x32_bf16 v[10:13], v[182:185], v[216:219], v[10:13]
	v_mfma_f32_16x16x32_bf16 v[6:9], v[174:177], v[224:227], v[6:9]
	v_mfma_f32_16x16x32_bf16 v[2:5], v[182:185], v[224:227], v[2:5]
	s_setprio 0
	s_barrier
	s_add_i32 s9, 0, 0x18000
	v_add_u32_e32 v0, s9, v189
	s_add_i32 s78, 0, 0x1c000
	ds_read_b128 v[130:133], v0
	ds_read_b128 v[134:137], v0 offset:1024
	ds_read_b128 v[162:165], v0 offset:2048
	ds_read_b128 v[166:169], v0 offset:3072
	v_add_u32_e32 v0, s78, v189
	ds_read_b128 v[170:173], v0
	ds_read_b128 v[174:177], v0 offset:1024
	ds_read_b128 v[178:181], v0 offset:2048
	ds_read_b128 v[182:185], v0 offset:3072
	s_add_u32 s26, s26, 0x40000
	s_addc_u32 s27, s27, 0
	s_mov_b32 m0, s42
	v_lshl_add_u64 v[230:231], s[26:27], 0, v[144:145]
	ds_read_b128 v[196:199], v193 offset:32768
	ds_read_b128 v[200:203], v193 offset:33792
	ds_read_b128 v[204:207], v193 offset:34816
	ds_read_b128 v[208:211], v193 offset:35840
	ds_read_b128 v[212:215], v193 offset:36864
	ds_read_b128 v[216:219], v193 offset:37888
	ds_read_b128 v[220:223], v193 offset:38912
	ds_read_b128 v[224:227], v193 offset:39936
	global_load_lds_dwordx4 v[230:231], off
	v_lshl_add_u64 v[230:231], s[26:27], 0, v[140:141]
	s_mov_b32 m0, s43
	s_nop 0
	global_load_lds_dwordx4 v[230:231], off
	s_waitcnt vmcnt(8)
	s_waitcnt lgkmcnt(0)
	s_barrier
	s_setprio 1
	v_mfma_f32_16x16x32_bf16 v[126:129], v[130:133], v[196:199], v[126:129]
	v_mfma_f32_16x16x32_bf16 v[122:125], v[162:165], v[196:199], v[122:125]
	v_mfma_f32_16x16x32_bf16 v[118:121], v[130:133], v[204:207], v[118:121]
	v_mfma_f32_16x16x32_bf16 v[114:117], v[162:165], v[204:207], v[114:117]
	v_mfma_f32_16x16x32_bf16 v[102:105], v[130:133], v[212:215], v[102:105]
	v_mfma_f32_16x16x32_bf16 v[98:101], v[162:165], v[212:215], v[98:101]
	v_mfma_f32_16x16x32_bf16 v[86:89], v[130:133], v[220:223], v[86:89]
	v_mfma_f32_16x16x32_bf16 v[82:85], v[162:165], v[220:223], v[82:85]
	v_mfma_f32_16x16x32_bf16 v[126:129], v[134:137], v[200:203], v[126:129]
	v_mfma_f32_16x16x32_bf16 v[122:125], v[166:169], v[200:203], v[122:125]
	v_mfma_f32_16x16x32_bf16 v[118:121], v[134:137], v[208:211], v[118:121]
	v_mfma_f32_16x16x32_bf16 v[114:117], v[166:169], v[208:211], v[114:117]
	v_mfma_f32_16x16x32_bf16 v[102:105], v[134:137], v[216:219], v[102:105]
	v_mfma_f32_16x16x32_bf16 v[98:101], v[166:169], v[216:219], v[98:101]
	v_mfma_f32_16x16x32_bf16 v[86:89], v[134:137], v[224:227], v[86:89]
	v_mfma_f32_16x16x32_bf16 v[82:85], v[166:169], v[224:227], v[82:85]
	v_mfma_f32_16x16x32_bf16 v[110:113], v[170:173], v[196:199], v[110:113]
	v_mfma_f32_16x16x32_bf16 v[106:109], v[178:181], v[196:199], v[106:109]
	v_mfma_f32_16x16x32_bf16 v[94:97], v[170:173], v[204:207], v[94:97]
	v_mfma_f32_16x16x32_bf16 v[90:93], v[178:181], v[204:207], v[90:93]
	v_mfma_f32_16x16x32_bf16 v[78:81], v[170:173], v[212:215], v[78:81]
	v_mfma_f32_16x16x32_bf16 v[74:77], v[178:181], v[212:215], v[74:77]
	v_mfma_f32_16x16x32_bf16 v[70:73], v[170:173], v[220:223], v[70:73]
	v_mfma_f32_16x16x32_bf16 v[66:69], v[178:181], v[220:223], v[66:69]
	v_mfma_f32_16x16x32_bf16 v[110:113], v[174:177], v[200:203], v[110:113]
	v_mfma_f32_16x16x32_bf16 v[106:109], v[182:185], v[200:203], v[106:109]
	v_mfma_f32_16x16x32_bf16 v[94:97], v[174:177], v[208:211], v[94:97]
	v_mfma_f32_16x16x32_bf16 v[90:93], v[182:185], v[208:211], v[90:93]
	v_mfma_f32_16x16x32_bf16 v[78:81], v[174:177], v[216:219], v[78:81]
	v_mfma_f32_16x16x32_bf16 v[74:77], v[182:185], v[216:219], v[74:77]
	v_mfma_f32_16x16x32_bf16 v[70:73], v[174:177], v[224:227], v[70:73]
	v_mfma_f32_16x16x32_bf16 v[66:69], v[182:185], v[224:227], v[66:69]
	s_setprio 0
	s_barrier
	s_add_i32 s9, s9, s29
	v_lshl_add_u64 v[148:149], v[148:149], 0, s[70:71]
	s_mov_b32 m0, s9
	ds_read_b128 v[196:199], v193 offset:49152
	ds_read_b128 v[200:203], v193 offset:50176
	ds_read_b128 v[204:207], v193 offset:51200
	ds_read_b128 v[208:211], v193 offset:52224
	ds_read_b128 v[212:215], v193 offset:53248
	ds_read_b128 v[216:219], v193 offset:54272
	ds_read_b128 v[220:223], v193 offset:55296
	ds_read_b128 v[224:227], v193 offset:56320
	global_load_lds_dwordx4 v[148:149], off
	s_add_i32 m0, s9, 0x2000
	s_add_u32 s6, s6, 0x40080
	v_lshl_add_u64 v[148:149], v[150:151], 0, s[70:71]
	s_addc_u32 s7, s7, 0
	s_add_i32 s9, s78, s29
	global_load_lds_dwordx4 v[148:149], off
	v_lshl_add_u64 v[148:149], s[6:7], 0, v[142:143]
	s_mov_b32 m0, s9
	s_nop 0
	global_load_lds_dwordx4 v[148:149], off
	v_lshl_add_u64 v[148:149], s[6:7], 0, v[138:139]
	s_add_i32 m0, s9, 0x2000
	s_nop 0
	global_load_lds_dwordx4 v[148:149], off
	v_lshl_add_u64 v[148:149], v[186:187], 0, s[70:71]
	s_mov_b32 m0, s44
	s_nop 0
	global_load_lds_dwordx4 v[148:149], off
	v_lshl_add_u64 v[148:149], v[228:229], 0, s[70:71]
	s_mov_b32 m0, s45
	s_nop 0
	global_load_lds_dwordx4 v[148:149], off
	s_waitcnt vmcnt(8)
	s_waitcnt lgkmcnt(0)
	s_barrier
	s_setprio 1
	v_mfma_f32_16x16x32_bf16 v[62:65], v[130:133], v[196:199], v[62:65]
	v_mfma_f32_16x16x32_bf16 v[58:61], v[162:165], v[196:199], v[58:61]
	v_mfma_f32_16x16x32_bf16 v[54:57], v[130:133], v[204:207], v[54:57]
	v_mfma_f32_16x16x32_bf16 v[50:53], v[162:165], v[204:207], v[50:53]
	v_mfma_f32_16x16x32_bf16 v[38:41], v[130:133], v[212:215], v[38:41]
	v_mfma_f32_16x16x32_bf16 v[34:37], v[162:165], v[212:215], v[34:37]
	v_mfma_f32_16x16x32_bf16 v[22:25], v[130:133], v[220:223], v[22:25]
	v_mfma_f32_16x16x32_bf16 v[18:21], v[162:165], v[220:223], v[18:21]
	v_mfma_f32_16x16x32_bf16 v[62:65], v[134:137], v[200:203], v[62:65]
	v_mfma_f32_16x16x32_bf16 v[58:61], v[166:169], v[200:203], v[58:61]
	v_mfma_f32_16x16x32_bf16 v[54:57], v[134:137], v[208:211], v[54:57]
	v_mfma_f32_16x16x32_bf16 v[50:53], v[166:169], v[208:211], v[50:53]
	v_mfma_f32_16x16x32_bf16 v[38:41], v[134:137], v[216:219], v[38:41]
	v_mfma_f32_16x16x32_bf16 v[34:37], v[166:169], v[216:219], v[34:37]
	v_mfma_f32_16x16x32_bf16 v[22:25], v[134:137], v[224:227], v[22:25]
	v_mfma_f32_16x16x32_bf16 v[18:21], v[166:169], v[224:227], v[18:21]
	v_mfma_f32_16x16x32_bf16 v[46:49], v[170:173], v[196:199], v[46:49]
	v_mfma_f32_16x16x32_bf16 v[42:45], v[178:181], v[196:199], v[42:45]
	v_mfma_f32_16x16x32_bf16 v[30:33], v[170:173], v[204:207], v[30:33]
	v_mfma_f32_16x16x32_bf16 v[26:29], v[178:181], v[204:207], v[26:29]
	v_mfma_f32_16x16x32_bf16 v[14:17], v[170:173], v[212:215], v[14:17]
	v_mfma_f32_16x16x32_bf16 v[10:13], v[178:181], v[212:215], v[10:13]
	v_mfma_f32_16x16x32_bf16 v[6:9], v[170:173], v[220:223], v[6:9]
	v_mfma_f32_16x16x32_bf16 v[2:5], v[178:181], v[220:223], v[2:5]
	v_mfma_f32_16x16x32_bf16 v[46:49], v[174:177], v[200:203], v[46:49]
	v_mfma_f32_16x16x32_bf16 v[42:45], v[182:185], v[200:203], v[42:45]
	v_mfma_f32_16x16x32_bf16 v[30:33], v[174:177], v[208:211], v[30:33]
	v_mfma_f32_16x16x32_bf16 v[26:29], v[182:185], v[208:211], v[26:29]
	v_mfma_f32_16x16x32_bf16 v[14:17], v[174:177], v[216:219], v[14:17]
	v_mfma_f32_16x16x32_bf16 v[10:13], v[182:185], v[216:219], v[10:13]
	v_mfma_f32_16x16x32_bf16 v[6:9], v[174:177], v[224:227], v[6:9]
	v_mfma_f32_16x16x32_bf16 v[2:5], v[182:185], v[224:227], v[2:5]
	s_setprio 0
	s_barrier
	s_add_i32 s53, s53, 2
	s_add_u32 s4, s4, 0x100
	s_addc_u32 s5, s5, 0
	s_add_u32 s51, s51, 0x100
	s_addc_u32 s52, s52, 0
	s_cmp_gt_u32 s53, 13
	s_cbranch_scc0 .LBB0_182
	s_and_b64 vcc, exec, s[36:37]
	s_cbranch_vccz .LBB0_185
	s_barrier

.LBB0_220:
	s_add_u32 s9, s36, 0xfffc0080
	s_addc_u32 s26, s37, -1
	s_add_i32 s60, 0, 0x10000
	s_cmp_eq_u32 s53, 12
	s_cselect_b32 s39, s19, s26
	s_cselect_b32 s38, s49, s9
	v_add_u32_e32 v148, s60, v141
	s_cselect_b32 s27, s17, s52
	s_cselect_b32 s26, s50, s51
	s_add_i32 s9, 0, 0x14000
	ds_read_b128 v[144:147], v148
	ds_read_b128 v[156:159], v148 offset:1024
	ds_read_b128 v[160:163], v148 offset:2048
	ds_read_b128 v[164:167], v148 offset:3072
	v_add_u32_e32 v148, s9, v141
	ds_read_b128 v[168:171], v148
	ds_read_b128 v[172:175], v148 offset:1024
	ds_read_b128 v[176:179], v148 offset:2048
	ds_read_b128 v[180:183], v148 offset:3072
	v_lshl_add_u64 v[148:149], s[36:37], 0, v[136:137]
	s_add_i32 m0, s40, 0xc000
	ds_read_b128 v[184:187], v143
	ds_read_b128 v[188:191], v143 offset:1024
	ds_read_b128 v[192:195], v143 offset:2048
	ds_read_b128 v[196:199], v143 offset:3072
	ds_read_b128 v[200:203], v143 offset:4096
	ds_read_b128 v[204:207], v143 offset:5120
	ds_read_b128 v[208:211], v143 offset:6144
	ds_read_b128 v[212:215], v143 offset:7168
	global_load_lds_dwordx4 v[148:149], off
	v_lshl_add_u64 v[148:149], s[36:37], 0, v[138:139]
	s_add_i32 m0, s40, 0xe000
	s_nop 0
	global_load_lds_dwordx4 v[148:149], off
	s_waitcnt vmcnt(8)
	s_waitcnt lgkmcnt(0)
	s_barrier
	s_setprio 1
	v_mfma_f32_16x16x32_bf16 v[126:129], v[144:147], v[184:187], v[126:129]
	v_mfma_f32_16x16x32_bf16 v[122:125], v[160:163], v[184:187], v[122:125]
	v_mfma_f32_16x16x32_bf16 v[118:121], v[144:147], v[192:195], v[118:121]
	v_mfma_f32_16x16x32_bf16 v[114:117], v[160:163], v[192:195], v[114:117]
	v_mfma_f32_16x16x32_bf16 v[102:105], v[144:147], v[200:203], v[102:105]
	v_mfma_f32_16x16x32_bf16 v[98:101], v[160:163], v[200:203], v[98:101]
	v_mfma_f32_16x16x32_bf16 v[86:89], v[144:147], v[208:211], v[86:89]
	v_mfma_f32_16x16x32_bf16 v[82:85], v[160:163], v[208:211], v[82:85]
	v_mfma_f32_16x16x32_bf16 v[126:129], v[156:159], v[188:191], v[126:129]
	v_mfma_f32_16x16x32_bf16 v[122:125], v[164:167], v[188:191], v[122:125]
	v_mfma_f32_16x16x32_bf16 v[118:121], v[156:159], v[196:199], v[118:121]
	v_mfma_f32_16x16x32_bf16 v[114:117], v[164:167], v[196:199], v[114:117]
	v_mfma_f32_16x16x32_bf16 v[102:105], v[156:159], v[204:207], v[102:105]
	v_mfma_f32_16x16x32_bf16 v[98:101], v[164:167], v[204:207], v[98:101]
	v_mfma_f32_16x16x32_bf16 v[86:89], v[156:159], v[212:215], v[86:89]
	v_mfma_f32_16x16x32_bf16 v[82:85], v[164:167], v[212:215], v[82:85]
	v_mfma_f32_16x16x32_bf16 v[110:113], v[168:171], v[184:187], v[110:113]
	v_mfma_f32_16x16x32_bf16 v[106:109], v[176:179], v[184:187], v[106:109]
	v_mfma_f32_16x16x32_bf16 v[94:97], v[168:171], v[192:195], v[94:97]
	v_mfma_f32_16x16x32_bf16 v[90:93], v[176:179], v[192:195], v[90:93]
	v_mfma_f32_16x16x32_bf16 v[78:81], v[168:171], v[200:203], v[78:81]
	v_mfma_f32_16x16x32_bf16 v[74:77], v[176:179], v[200:203], v[74:77]
	v_mfma_f32_16x16x32_bf16 v[70:73], v[168:171], v[208:211], v[70:73]
	v_mfma_f32_16x16x32_bf16 v[66:69], v[176:179], v[208:211], v[66:69]
	v_mfma_f32_16x16x32_bf16 v[110:113], v[172:175], v[188:191], v[110:113]
	v_mfma_f32_16x16x32_bf16 v[106:109], v[180:183], v[188:191], v[106:109]
	v_mfma_f32_16x16x32_bf16 v[94:97], v[172:175], v[196:199], v[94:97]
	v_mfma_f32_16x16x32_bf16 v[90:93], v[180:183], v[196:199], v[90:93]
	v_mfma_f32_16x16x32_bf16 v[78:81], v[172:175], v[204:207], v[78:81]
	v_mfma_f32_16x16x32_bf16 v[74:77], v[180:183], v[204:207], v[74:77]
	v_mfma_f32_16x16x32_bf16 v[70:73], v[172:175], v[212:215], v[70:73]
	v_mfma_f32_16x16x32_bf16 v[66:69], v[180:183], v[212:215], v[66:69]
	s_setprio 0
	s_barrier
	s_add_i32 s60, s60, s29
	v_lshl_add_u64 v[148:149], s[26:27], 0, v[0:1]
	s_mov_b32 m0, s60
	ds_read_b128 v[184:187], v143 offset:16384
	ds_read_b128 v[188:191], v143 offset:17408
	ds_read_b128 v[192:195], v143 offset:18432
	ds_read_b128 v[196:199], v143 offset:19456
	ds_read_b128 v[200:203], v143 offset:20480
	ds_read_b128 v[204:207], v143 offset:21504
	ds_read_b128 v[208:211], v143 offset:22528
	ds_read_b128 v[212:215], v143 offset:23552
	global_load_lds_dwordx4 v[148:149], off
	s_add_i32 m0, s60, 0x2000
	s_add_u32 s60, s26, 0x40000
	v_lshl_add_u64 v[150:151], s[26:27], 0, v[130:131]
	s_addc_u32 s61, s27, 0
	s_add_i32 s9, s9, s29
	global_load_lds_dwordx4 v[150:151], off
	v_lshl_add_u64 v[216:217], s[60:61], 0, v[0:1]
	s_mov_b32 m0, s9
	v_lshl_add_u64 v[218:219], s[38:39], 0, v[132:133]
	global_load_lds_dwordx4 v[216:217], off
	v_lshl_add_u64 v[216:217], s[60:61], 0, v[130:131]
	s_add_i32 m0, s9, 0x2000
	s_nop 0
	global_load_lds_dwordx4 v[216:217], off
	v_lshl_add_u64 v[216:217], s[38:39], 0, v[134:135]
	s_mov_b32 m0, s40
	s_nop 0
	global_load_lds_dwordx4 v[216:217], off
	s_mov_b32 m0, s41
	s_nop 0
	global_load_lds_dwordx4 v[218:219], off
	s_waitcnt vmcnt(8)
	s_waitcnt lgkmcnt(0)
	s_barrier
	s_setprio 1
	v_mfma_f32_16x16x32_bf16 v[62:65], v[144:147], v[184:187], v[62:65]
	v_mfma_f32_16x16x32_bf16 v[58:61], v[160:163], v[184:187], v[58:61]
	v_mfma_f32_16x16x32_bf16 v[54:57], v[144:147], v[192:195], v[54:57]
	v_mfma_f32_16x16x32_bf16 v[50:53], v[160:163], v[192:195], v[50:53]
	v_mfma_f32_16x16x32_bf16 v[38:41], v[144:147], v[200:203], v[38:41]
	v_mfma_f32_16x16x32_bf16 v[34:37], v[160:163], v[200:203], v[34:37]
	v_mfma_f32_16x16x32_bf16 v[22:25], v[144:147], v[208:211], v[22:25]
	v_mfma_f32_16x16x32_bf16 v[18:21], v[160:163], v[208:211], v[18:21]
	v_mfma_f32_16x16x32_bf16 v[62:65], v[156:159], v[188:191], v[62:65]
	v_mfma_f32_16x16x32_bf16 v[58:61], v[164:167], v[188:191], v[58:61]
	v_mfma_f32_16x16x32_bf16 v[54:57], v[156:159], v[196:199], v[54:57]
	v_mfma_f32_16x16x32_bf16 v[50:53], v[164:167], v[196:199], v[50:53]
	v_mfma_f32_16x16x32_bf16 v[38:41], v[156:159], v[204:207], v[38:41]
	v_mfma_f32_16x16x32_bf16 v[34:37], v[164:167], v[204:207], v[34:37]
	v_mfma_f32_16x16x32_bf16 v[22:25], v[156:159], v[212:215], v[22:25]
	v_mfma_f32_16x16x32_bf16 v[18:21], v[164:167], v[212:215], v[18:21]
	v_mfma_f32_16x16x32_bf16 v[46:49], v[168:171], v[184:187], v[46:49]
	v_mfma_f32_16x16x32_bf16 v[42:45], v[176:179], v[184:187], v[42:45]
	v_mfma_f32_16x16x32_bf16 v[30:33], v[168:171], v[192:195], v[30:33]
	v_mfma_f32_16x16x32_bf16 v[26:29], v[176:179], v[192:195], v[26:29]
	v_mfma_f32_16x16x32_bf16 v[14:17], v[168:171], v[200:203], v[14:17]
	v_mfma_f32_16x16x32_bf16 v[10:13], v[176:179], v[200:203], v[10:13]
	v_mfma_f32_16x16x32_bf16 v[6:9], v[168:171], v[208:211], v[6:9]
	v_mfma_f32_16x16x32_bf16 v[2:5], v[176:179], v[208:211], v[2:5]
	v_mfma_f32_16x16x32_bf16 v[46:49], v[172:175], v[188:191], v[46:49]
	v_mfma_f32_16x16x32_bf16 v[42:45], v[180:183], v[188:191], v[42:45]
	v_mfma_f32_16x16x32_bf16 v[30:33], v[172:175], v[196:199], v[30:33]
	v_mfma_f32_16x16x32_bf16 v[26:29], v[180:183], v[196:199], v[26:29]
	v_mfma_f32_16x16x32_bf16 v[14:17], v[172:175], v[204:207], v[14:17]
	v_mfma_f32_16x16x32_bf16 v[10:13], v[180:183], v[204:207], v[10:13]
	v_mfma_f32_16x16x32_bf16 v[6:9], v[172:175], v[212:215], v[6:9]
	v_mfma_f32_16x16x32_bf16 v[2:5], v[180:183], v[212:215], v[2:5]
	s_setprio 0
	s_barrier
	s_add_i32 s9, 0, 0x18000
	s_add_i32 s60, 0, 0x1c000
	v_add_u32_e32 v164, s9, v141
	v_add_u32_e32 v180, s60, v141
	ds_read_b128 v[144:147], v164
	ds_read_b128 v[156:159], v164 offset:1024
	ds_read_b128 v[160:163], v164 offset:2048
	ds_read_b128 v[164:167], v164 offset:3072
	ds_read_b128 v[168:171], v180
	ds_read_b128 v[172:175], v180 offset:1024
	ds_read_b128 v[176:179], v180 offset:2048
	ds_read_b128 v[180:183], v180 offset:3072
	s_add_u32 s38, s38, 0x40000
	s_addc_u32 s39, s39, 0
	s_mov_b32 m0, s42
	v_lshl_add_u64 v[220:221], s[38:39], 0, v[134:135]
	ds_read_b128 v[184:187], v143 offset:32768
	ds_read_b128 v[188:191], v143 offset:33792
	ds_read_b128 v[192:195], v143 offset:34816
	ds_read_b128 v[196:199], v143 offset:35840
	ds_read_b128 v[200:203], v143 offset:36864
	ds_read_b128 v[204:207], v143 offset:37888
	ds_read_b128 v[208:211], v143 offset:38912
	ds_read_b128 v[212:215], v143 offset:39936
	global_load_lds_dwordx4 v[220:221], off
	v_lshl_add_u64 v[220:221], s[38:39], 0, v[132:133]
	s_mov_b32 m0, s43
	s_nop 0
	global_load_lds_dwordx4 v[220:221], off
	s_waitcnt vmcnt(8)
	s_waitcnt lgkmcnt(0)
	s_barrier
	s_setprio 1
	v_mfma_f32_16x16x32_bf16 v[126:129], v[144:147], v[184:187], v[126:129]
	v_mfma_f32_16x16x32_bf16 v[122:125], v[160:163], v[184:187], v[122:125]
	v_mfma_f32_16x16x32_bf16 v[118:121], v[144:147], v[192:195], v[118:121]
	v_mfma_f32_16x16x32_bf16 v[114:117], v[160:163], v[192:195], v[114:117]
	v_mfma_f32_16x16x32_bf16 v[102:105], v[144:147], v[200:203], v[102:105]
	v_mfma_f32_16x16x32_bf16 v[98:101], v[160:163], v[200:203], v[98:101]
	v_mfma_f32_16x16x32_bf16 v[86:89], v[144:147], v[208:211], v[86:89]
	v_mfma_f32_16x16x32_bf16 v[82:85], v[160:163], v[208:211], v[82:85]
	v_mfma_f32_16x16x32_bf16 v[126:129], v[156:159], v[188:191], v[126:129]
	v_mfma_f32_16x16x32_bf16 v[122:125], v[164:167], v[188:191], v[122:125]
	v_mfma_f32_16x16x32_bf16 v[118:121], v[156:159], v[196:199], v[118:121]
	v_mfma_f32_16x16x32_bf16 v[114:117], v[164:167], v[196:199], v[114:117]
	v_mfma_f32_16x16x32_bf16 v[102:105], v[156:159], v[204:207], v[102:105]
	v_mfma_f32_16x16x32_bf16 v[98:101], v[164:167], v[204:207], v[98:101]
	v_mfma_f32_16x16x32_bf16 v[86:89], v[156:159], v[212:215], v[86:89]
	v_mfma_f32_16x16x32_bf16 v[82:85], v[164:167], v[212:215], v[82:85]
	v_mfma_f32_16x16x32_bf16 v[110:113], v[168:171], v[184:187], v[110:113]
	v_mfma_f32_16x16x32_bf16 v[106:109], v[176:179], v[184:187], v[106:109]
	v_mfma_f32_16x16x32_bf16 v[94:97], v[168:171], v[192:195], v[94:97]
	v_mfma_f32_16x16x32_bf16 v[90:93], v[176:179], v[192:195], v[90:93]
	v_mfma_f32_16x16x32_bf16 v[78:81], v[168:171], v[200:203], v[78:81]
	v_mfma_f32_16x16x32_bf16 v[74:77], v[176:179], v[200:203], v[74:77]
	v_mfma_f32_16x16x32_bf16 v[70:73], v[168:171], v[208:211], v[70:73]
	v_mfma_f32_16x16x32_bf16 v[66:69], v[176:179], v[208:211], v[66:69]
	v_mfma_f32_16x16x32_bf16 v[110:113], v[172:175], v[188:191], v[110:113]
	v_mfma_f32_16x16x32_bf16 v[106:109], v[180:183], v[188:191], v[106:109]
	v_mfma_f32_16x16x32_bf16 v[94:97], v[172:175], v[196:199], v[94:97]
	v_mfma_f32_16x16x32_bf16 v[90:93], v[180:183], v[196:199], v[90:93]
	v_mfma_f32_16x16x32_bf16 v[78:81], v[172:175], v[204:207], v[78:81]
	v_mfma_f32_16x16x32_bf16 v[74:77], v[180:183], v[204:207], v[74:77]
	v_mfma_f32_16x16x32_bf16 v[70:73], v[172:175], v[212:215], v[70:73]
	v_mfma_f32_16x16x32_bf16 v[66:69], v[180:183], v[212:215], v[66:69]
	s_setprio 0
	s_barrier
	s_add_i32 s9, s9, s29
	v_lshl_add_u64 v[148:149], v[148:149], 0, s[70:71]
	s_mov_b32 m0, s9
	ds_read_b128 v[184:187], v143 offset:49152
	ds_read_b128 v[188:191], v143 offset:50176
	ds_read_b128 v[192:195], v143 offset:51200
	ds_read_b128 v[196:199], v143 offset:52224
	ds_read_b128 v[200:203], v143 offset:53248
	ds_read_b128 v[204:207], v143 offset:54272
	ds_read_b128 v[208:211], v143 offset:55296
	ds_read_b128 v[212:215], v143 offset:56320
	global_load_lds_dwordx4 v[148:149], off
	s_add_i32 m0, s9, 0x2000
	s_add_u32 s26, s26, 0x40080
	v_lshl_add_u64 v[148:149], v[150:151], 0, s[70:71]
	s_addc_u32 s27, s27, 0
	s_add_i32 s9, s60, s29
	global_load_lds_dwordx4 v[148:149], off
	v_lshl_add_u64 v[148:149], s[26:27], 0, v[0:1]
	s_mov_b32 m0, s9
	s_nop 0
	global_load_lds_dwordx4 v[148:149], off
	v_lshl_add_u64 v[148:149], s[26:27], 0, v[130:131]
	s_add_i32 m0, s9, 0x2000
	s_nop 0
	global_load_lds_dwordx4 v[148:149], off
	v_lshl_add_u64 v[148:149], v[216:217], 0, s[70:71]
	s_mov_b32 m0, s44
	s_nop 0
	global_load_lds_dwordx4 v[148:149], off
	v_lshl_add_u64 v[148:149], v[218:219], 0, s[70:71]
	s_mov_b32 m0, s45
	s_nop 0
	global_load_lds_dwordx4 v[148:149], off
	s_waitcnt vmcnt(8)
	s_waitcnt lgkmcnt(0)
	s_barrier
	s_setprio 1
	v_mfma_f32_16x16x32_bf16 v[62:65], v[144:147], v[184:187], v[62:65]
	v_mfma_f32_16x16x32_bf16 v[58:61], v[160:163], v[184:187], v[58:61]
	v_mfma_f32_16x16x32_bf16 v[54:57], v[144:147], v[192:195], v[54:57]
	v_mfma_f32_16x16x32_bf16 v[50:53], v[160:163], v[192:195], v[50:53]
	v_mfma_f32_16x16x32_bf16 v[38:41], v[144:147], v[200:203], v[38:41]
	v_mfma_f32_16x16x32_bf16 v[34:37], v[160:163], v[200:203], v[34:37]
	v_mfma_f32_16x16x32_bf16 v[22:25], v[144:147], v[208:211], v[22:25]
	v_mfma_f32_16x16x32_bf16 v[18:21], v[160:163], v[208:211], v[18:21]
	v_mfma_f32_16x16x32_bf16 v[62:65], v[156:159], v[188:191], v[62:65]
	v_mfma_f32_16x16x32_bf16 v[58:61], v[164:167], v[188:191], v[58:61]
	v_mfma_f32_16x16x32_bf16 v[54:57], v[156:159], v[196:199], v[54:57]
	v_mfma_f32_16x16x32_bf16 v[50:53], v[164:167], v[196:199], v[50:53]
	v_mfma_f32_16x16x32_bf16 v[38:41], v[156:159], v[204:207], v[38:41]
	v_mfma_f32_16x16x32_bf16 v[34:37], v[164:167], v[204:207], v[34:37]
	v_mfma_f32_16x16x32_bf16 v[22:25], v[156:159], v[212:215], v[22:25]
	v_mfma_f32_16x16x32_bf16 v[18:21], v[164:167], v[212:215], v[18:21]
	v_mfma_f32_16x16x32_bf16 v[46:49], v[168:171], v[184:187], v[46:49]
	v_mfma_f32_16x16x32_bf16 v[42:45], v[176:179], v[184:187], v[42:45]
	v_mfma_f32_16x16x32_bf16 v[30:33], v[168:171], v[192:195], v[30:33]
	v_mfma_f32_16x16x32_bf16 v[26:29], v[176:179], v[192:195], v[26:29]
	v_mfma_f32_16x16x32_bf16 v[14:17], v[168:171], v[200:203], v[14:17]
	v_mfma_f32_16x16x32_bf16 v[10:13], v[176:179], v[200:203], v[10:13]
	v_mfma_f32_16x16x32_bf16 v[6:9], v[168:171], v[208:211], v[6:9]
	v_mfma_f32_16x16x32_bf16 v[2:5], v[176:179], v[208:211], v[2:5]
	v_mfma_f32_16x16x32_bf16 v[46:49], v[172:175], v[188:191], v[46:49]
	v_mfma_f32_16x16x32_bf16 v[42:45], v[180:183], v[188:191], v[42:45]
	v_mfma_f32_16x16x32_bf16 v[30:33], v[172:175], v[196:199], v[30:33]
	v_mfma_f32_16x16x32_bf16 v[26:29], v[180:183], v[196:199], v[26:29]
	v_mfma_f32_16x16x32_bf16 v[14:17], v[172:175], v[204:207], v[14:17]
	v_mfma_f32_16x16x32_bf16 v[10:13], v[180:183], v[204:207], v[10:13]
	v_mfma_f32_16x16x32_bf16 v[6:9], v[172:175], v[212:215], v[6:9]
	v_mfma_f32_16x16x32_bf16 v[2:5], v[180:183], v[212:215], v[2:5]
	s_setprio 0
	s_barrier
	s_add_i32 s53, s53, 2
	s_add_u32 s36, s36, 0x100
	s_addc_u32 s37, s37, 0
	s_add_u32 s51, s51, 0x100
	s_addc_u32 s52, s52, 0
	s_cmp_gt_u32 s53, 13
	s_cbranch_scc0 .LBB0_220
	s_and_b64 vcc, exec, s[14:15]
	s_cbranch_vccz .LBB0_223
	s_barrier

.LBB0_376:
	s_add_u32 s53, s18, s9
	s_addc_u32 s74, s19, 0
	s_add_u32 s60, s53, 0x100
	s_addc_u32 s61, s74, 0
	s_and_b64 s[26:27], s[38:39], exec
	s_cselect_b32 s61, s25, s61
	s_cselect_b32 s60, s24, s60
	s_add_u32 s9, s16, s9
	s_addc_u32 s26, s17, 0
	s_add_u32 s9, s9, 0x100
	s_addc_u32 s72, s26, 0
	s_add_i32 s92, 0, 0x10000
	s_and_b64 s[26:27], s[38:39], exec
	s_cselect_b32 s73, s23, s72
	s_cselect_b32 s72, s52, s9
	s_add_i32 s39, 0, 0x14000
	s_add_u32 vcc_lo, s53, 0x58080
	s_addc_u32 vcc_hi, s74, 0
	s_add_i32 s78, s92, s41
	s_add_i32 m0, s42, 0xc000
	s_add_i32 s93, s42, 0xe000
	s_add_i32 s91, s78, 0x2000
	v_add_u32_e32 v148, s92, v137
	s_add_u32 s74, s72, 0x10000
	ds_read_b128 v[140:143], v148
	ds_read_b128 v[144:147], v148 offset:1024
	ds_read_b128 v[156:159], v148 offset:2048
	ds_read_b128 v[160:163], v148 offset:3072
	v_add_u32_e32 v148, s39, v137
	s_addc_u32 s75, s73, 0
	s_add_i32 s79, s39, s41
	ds_read_b128 v[164:167], v148
	ds_read_b128 v[168:171], v148 offset:1024
	ds_read_b128 v[172:175], v148 offset:2048
	ds_read_b128 v[176:179], v148 offset:3072
	s_add_i32 s90, s79, 0x2000
	s_add_i32 s97, 0, 0x18000
	s_add_i32 s83, 0, 0x1c000
	s_add_u32 s26, s60, 0x58000
	s_addc_u32 s27, s61, 0
	s_add_i32 s53, s97, s41
	s_add_i32 s9, s53, 0x2000
	s_add_u32 s38, s72, 0x10080
	s_addc_u32 s39, s73, 0
	s_add_i32 s96, s83, s41
	s_add_i32 s92, s96, 0x2000
	v_lshl_add_u64 v[148:149], vcc, 0, v[134:135]
	ds_read_b128 v[180:183], v139
	ds_read_b128 v[184:187], v139 offset:1024
	ds_read_b128 v[188:191], v139 offset:2048
	ds_read_b128 v[192:195], v139 offset:3072
	ds_read_b128 v[196:199], v139 offset:4096
	ds_read_b128 v[200:203], v139 offset:5120
	ds_read_b128 v[204:207], v139 offset:6144
	ds_read_b128 v[208:211], v139 offset:7168
	global_load_lds_dwordx4 v[148:149], off
	v_lshl_add_u64 v[148:149], vcc, 0, v[132:133]
	s_mov_b32 m0, s93
	s_nop 0
	global_load_lds_dwordx4 v[148:149], off
	s_waitcnt vmcnt(8)
	s_waitcnt lgkmcnt(0)
	s_barrier
	s_setprio 1
	v_mfma_f32_16x16x32_bf16 v[126:129], v[140:143], v[180:183], v[126:129]
	v_mfma_f32_16x16x32_bf16 v[122:125], v[156:159], v[180:183], v[122:125]
	v_mfma_f32_16x16x32_bf16 v[118:121], v[140:143], v[188:191], v[118:121]
	v_mfma_f32_16x16x32_bf16 v[114:117], v[156:159], v[188:191], v[114:117]
	v_mfma_f32_16x16x32_bf16 v[102:105], v[140:143], v[196:199], v[102:105]
	v_mfma_f32_16x16x32_bf16 v[98:101], v[156:159], v[196:199], v[98:101]
	v_mfma_f32_16x16x32_bf16 v[86:89], v[140:143], v[204:207], v[86:89]
	v_mfma_f32_16x16x32_bf16 v[82:85], v[156:159], v[204:207], v[82:85]
	v_mfma_f32_16x16x32_bf16 v[126:129], v[144:147], v[184:187], v[126:129]
	v_mfma_f32_16x16x32_bf16 v[122:125], v[160:163], v[184:187], v[122:125]
	v_mfma_f32_16x16x32_bf16 v[118:121], v[144:147], v[192:195], v[118:121]
	v_mfma_f32_16x16x32_bf16 v[114:117], v[160:163], v[192:195], v[114:117]
	v_mfma_f32_16x16x32_bf16 v[102:105], v[144:147], v[200:203], v[102:105]
	v_mfma_f32_16x16x32_bf16 v[98:101], v[160:163], v[200:203], v[98:101]
	v_mfma_f32_16x16x32_bf16 v[86:89], v[144:147], v[208:211], v[86:89]
	v_mfma_f32_16x16x32_bf16 v[82:85], v[160:163], v[208:211], v[82:85]
	v_mfma_f32_16x16x32_bf16 v[110:113], v[164:167], v[180:183], v[110:113]
	v_mfma_f32_16x16x32_bf16 v[106:109], v[172:175], v[180:183], v[106:109]
	v_mfma_f32_16x16x32_bf16 v[94:97], v[164:167], v[188:191], v[94:97]
	v_mfma_f32_16x16x32_bf16 v[90:93], v[172:175], v[188:191], v[90:93]
	v_mfma_f32_16x16x32_bf16 v[78:81], v[164:167], v[196:199], v[78:81]
	v_mfma_f32_16x16x32_bf16 v[74:77], v[172:175], v[196:199], v[74:77]
	v_mfma_f32_16x16x32_bf16 v[70:73], v[164:167], v[204:207], v[70:73]
	v_mfma_f32_16x16x32_bf16 v[66:69], v[172:175], v[204:207], v[66:69]
	v_mfma_f32_16x16x32_bf16 v[110:113], v[168:171], v[184:187], v[110:113]
	v_mfma_f32_16x16x32_bf16 v[106:109], v[176:179], v[184:187], v[106:109]
	v_mfma_f32_16x16x32_bf16 v[94:97], v[168:171], v[192:195], v[94:97]
	v_mfma_f32_16x16x32_bf16 v[90:93], v[176:179], v[192:195], v[90:93]
	v_mfma_f32_16x16x32_bf16 v[78:81], v[168:171], v[200:203], v[78:81]
	v_mfma_f32_16x16x32_bf16 v[74:77], v[176:179], v[200:203], v[74:77]
	v_mfma_f32_16x16x32_bf16 v[70:73], v[168:171], v[208:211], v[70:73]
	v_mfma_f32_16x16x32_bf16 v[66:69], v[176:179], v[208:211], v[66:69]
	s_setprio 0
	s_barrier
	s_mov_b32 m0, s78
	v_lshl_add_u64 v[148:149], s[72:73], 0, v[0:1]
	ds_read_b128 v[180:183], v139 offset:16384
	ds_read_b128 v[184:187], v139 offset:17408
	ds_read_b128 v[188:191], v139 offset:18432
	ds_read_b128 v[192:195], v139 offset:19456
	ds_read_b128 v[196:199], v139 offset:20480
	ds_read_b128 v[200:203], v139 offset:21504
	ds_read_b128 v[204:207], v139 offset:22528
	ds_read_b128 v[208:211], v139 offset:23552
	global_load_lds_dwordx4 v[148:149], off
	v_lshl_add_u64 v[150:151], s[72:73], 0, v[130:131]
	s_mov_b32 m0, s91
	v_lshl_add_u64 v[212:213], s[74:75], 0, v[0:1]
	global_load_lds_dwordx4 v[150:151], off
	s_mov_b32 m0, s79
	v_lshl_add_u64 v[214:215], s[60:61], 0, v[132:133]
	global_load_lds_dwordx4 v[212:213], off
	v_lshl_add_u64 v[212:213], s[74:75], 0, v[130:131]
	s_mov_b32 m0, s90
	s_nop 0
	global_load_lds_dwordx4 v[212:213], off
	v_lshl_add_u64 v[212:213], s[60:61], 0, v[134:135]
	s_mov_b32 m0, s42
	s_nop 0
	global_load_lds_dwordx4 v[212:213], off
	s_mov_b32 m0, s43
	s_nop 0
	global_load_lds_dwordx4 v[214:215], off
	s_waitcnt vmcnt(8)
	s_waitcnt lgkmcnt(0)
	s_barrier
	s_setprio 1
	v_mfma_f32_16x16x32_bf16 v[62:65], v[140:143], v[180:183], v[62:65]
	v_mfma_f32_16x16x32_bf16 v[58:61], v[156:159], v[180:183], v[58:61]
	v_mfma_f32_16x16x32_bf16 v[54:57], v[140:143], v[188:191], v[54:57]
	v_mfma_f32_16x16x32_bf16 v[50:53], v[156:159], v[188:191], v[50:53]
	v_mfma_f32_16x16x32_bf16 v[38:41], v[140:143], v[196:199], v[38:41]
	v_mfma_f32_16x16x32_bf16 v[34:37], v[156:159], v[196:199], v[34:37]
	v_mfma_f32_16x16x32_bf16 v[22:25], v[140:143], v[204:207], v[22:25]
	v_mfma_f32_16x16x32_bf16 v[18:21], v[156:159], v[204:207], v[18:21]
	v_mfma_f32_16x16x32_bf16 v[62:65], v[144:147], v[184:187], v[62:65]
	v_mfma_f32_16x16x32_bf16 v[58:61], v[160:163], v[184:187], v[58:61]
	v_mfma_f32_16x16x32_bf16 v[54:57], v[144:147], v[192:195], v[54:57]
	v_mfma_f32_16x16x32_bf16 v[50:53], v[160:163], v[192:195], v[50:53]
	v_mfma_f32_16x16x32_bf16 v[38:41], v[144:147], v[200:203], v[38:41]
	v_mfma_f32_16x16x32_bf16 v[34:37], v[160:163], v[200:203], v[34:37]
	v_mfma_f32_16x16x32_bf16 v[22:25], v[144:147], v[208:211], v[22:25]
	v_mfma_f32_16x16x32_bf16 v[18:21], v[160:163], v[208:211], v[18:21]
	v_mfma_f32_16x16x32_bf16 v[46:49], v[164:167], v[180:183], v[46:49]
	v_mfma_f32_16x16x32_bf16 v[42:45], v[172:175], v[180:183], v[42:45]
	v_mfma_f32_16x16x32_bf16 v[30:33], v[164:167], v[188:191], v[30:33]
	v_mfma_f32_16x16x32_bf16 v[26:29], v[172:175], v[188:191], v[26:29]
	v_mfma_f32_16x16x32_bf16 v[14:17], v[164:167], v[196:199], v[14:17]
	v_mfma_f32_16x16x32_bf16 v[10:13], v[172:175], v[196:199], v[10:13]
	v_mfma_f32_16x16x32_bf16 v[6:9], v[164:167], v[204:207], v[6:9]
	v_mfma_f32_16x16x32_bf16 v[2:5], v[172:175], v[204:207], v[2:5]
	v_mfma_f32_16x16x32_bf16 v[46:49], v[168:171], v[184:187], v[46:49]
	v_mfma_f32_16x16x32_bf16 v[42:45], v[176:179], v[184:187], v[42:45]
	v_mfma_f32_16x16x32_bf16 v[30:33], v[168:171], v[192:195], v[30:33]
	v_mfma_f32_16x16x32_bf16 v[26:29], v[176:179], v[192:195], v[26:29]
	v_mfma_f32_16x16x32_bf16 v[14:17], v[168:171], v[200:203], v[14:17]
	v_mfma_f32_16x16x32_bf16 v[10:13], v[176:179], v[200:203], v[10:13]
	v_mfma_f32_16x16x32_bf16 v[6:9], v[168:171], v[208:211], v[6:9]
	v_mfma_f32_16x16x32_bf16 v[2:5], v[176:179], v[208:211], v[2:5]
	s_setprio 0
	s_barrier
	v_add_u32_e32 v160, s97, v137
	v_add_u32_e32 v176, s83, v137
	ds_read_b128 v[140:143], v160
	ds_read_b128 v[144:147], v160 offset:1024
	ds_read_b128 v[156:159], v160 offset:2048
	ds_read_b128 v[160:163], v160 offset:3072
	ds_read_b128 v[164:167], v176
	ds_read_b128 v[168:171], v176 offset:1024
	ds_read_b128 v[172:175], v176 offset:2048
	ds_read_b128 v[176:179], v176 offset:3072
	s_mov_b32 m0, s44
	v_lshl_add_u64 v[216:217], s[26:27], 0, v[134:135]
	ds_read_b128 v[180:183], v139 offset:32768
	ds_read_b128 v[184:187], v139 offset:33792
	ds_read_b128 v[188:191], v139 offset:34816
	ds_read_b128 v[192:195], v139 offset:35840
	ds_read_b128 v[196:199], v139 offset:36864
	ds_read_b128 v[200:203], v139 offset:37888
	ds_read_b128 v[204:207], v139 offset:38912
	ds_read_b128 v[208:211], v139 offset:39936
	global_load_lds_dwordx4 v[216:217], off
	v_lshl_add_u64 v[216:217], s[26:27], 0, v[132:133]
	s_mov_b32 m0, s45
	s_nop 0
	global_load_lds_dwordx4 v[216:217], off
	s_waitcnt vmcnt(8)
	s_waitcnt lgkmcnt(0)
	s_barrier
	s_setprio 1
	v_mfma_f32_16x16x32_bf16 v[126:129], v[140:143], v[180:183], v[126:129]
	v_mfma_f32_16x16x32_bf16 v[122:125], v[156:159], v[180:183], v[122:125]
	v_mfma_f32_16x16x32_bf16 v[118:121], v[140:143], v[188:191], v[118:121]
	v_mfma_f32_16x16x32_bf16 v[114:117], v[156:159], v[188:191], v[114:117]
	v_mfma_f32_16x16x32_bf16 v[102:105], v[140:143], v[196:199], v[102:105]
	v_mfma_f32_16x16x32_bf16 v[98:101], v[156:159], v[196:199], v[98:101]
	v_mfma_f32_16x16x32_bf16 v[86:89], v[140:143], v[204:207], v[86:89]
	v_mfma_f32_16x16x32_bf16 v[82:85], v[156:159], v[204:207], v[82:85]
	v_mfma_f32_16x16x32_bf16 v[126:129], v[144:147], v[184:187], v[126:129]
	v_mfma_f32_16x16x32_bf16 v[122:125], v[160:163], v[184:187], v[122:125]
	v_mfma_f32_16x16x32_bf16 v[118:121], v[144:147], v[192:195], v[118:121]
	v_mfma_f32_16x16x32_bf16 v[114:117], v[160:163], v[192:195], v[114:117]
	v_mfma_f32_16x16x32_bf16 v[102:105], v[144:147], v[200:203], v[102:105]
	v_mfma_f32_16x16x32_bf16 v[98:101], v[160:163], v[200:203], v[98:101]
	v_mfma_f32_16x16x32_bf16 v[86:89], v[144:147], v[208:211], v[86:89]
	v_mfma_f32_16x16x32_bf16 v[82:85], v[160:163], v[208:211], v[82:85]
	v_mfma_f32_16x16x32_bf16 v[110:113], v[164:167], v[180:183], v[110:113]
	v_mfma_f32_16x16x32_bf16 v[106:109], v[172:175], v[180:183], v[106:109]
	v_mfma_f32_16x16x32_bf16 v[94:97], v[164:167], v[188:191], v[94:97]
	v_mfma_f32_16x16x32_bf16 v[90:93], v[172:175], v[188:191], v[90:93]
	v_mfma_f32_16x16x32_bf16 v[78:81], v[164:167], v[196:199], v[78:81]
	v_mfma_f32_16x16x32_bf16 v[74:77], v[172:175], v[196:199], v[74:77]
	v_mfma_f32_16x16x32_bf16 v[70:73], v[164:167], v[204:207], v[70:73]
	v_mfma_f32_16x16x32_bf16 v[66:69], v[172:175], v[204:207], v[66:69]
	v_mfma_f32_16x16x32_bf16 v[110:113], v[168:171], v[184:187], v[110:113]
	v_mfma_f32_16x16x32_bf16 v[106:109], v[176:179], v[184:187], v[106:109]
	v_mfma_f32_16x16x32_bf16 v[94:97], v[168:171], v[192:195], v[94:97]
	v_mfma_f32_16x16x32_bf16 v[90:93], v[176:179], v[192:195], v[90:93]
	v_mfma_f32_16x16x32_bf16 v[78:81], v[168:171], v[200:203], v[78:81]
	v_mfma_f32_16x16x32_bf16 v[74:77], v[176:179], v[200:203], v[74:77]
	v_mfma_f32_16x16x32_bf16 v[70:73], v[168:171], v[208:211], v[70:73]
	v_mfma_f32_16x16x32_bf16 v[66:69], v[176:179], v[208:211], v[66:69]
	s_setprio 0
	s_barrier
	s_mov_b32 m0, s53
	v_lshl_add_u64 v[148:149], v[148:149], 0, s[70:71]
	ds_read_b128 v[180:183], v139 offset:49152
	ds_read_b128 v[184:187], v139 offset:50176
	ds_read_b128 v[188:191], v139 offset:51200
	ds_read_b128 v[192:195], v139 offset:52224
	ds_read_b128 v[196:199], v139 offset:53248
	ds_read_b128 v[200:203], v139 offset:54272
	ds_read_b128 v[204:207], v139 offset:55296
	ds_read_b128 v[208:211], v139 offset:56320
	global_load_lds_dwordx4 v[148:149], off
	v_lshl_add_u64 v[148:149], v[150:151], 0, s[70:71]
	s_mov_b32 m0, s9
	s_nop 0
	global_load_lds_dwordx4 v[148:149], off
	v_lshl_add_u64 v[148:149], s[38:39], 0, v[0:1]
	s_mov_b32 m0, s96
	s_nop 0
	global_load_lds_dwordx4 v[148:149], off
	v_lshl_add_u64 v[148:149], s[38:39], 0, v[130:131]
	s_mov_b32 m0, s92
	s_nop 0
	global_load_lds_dwordx4 v[148:149], off
	v_lshl_add_u64 v[148:149], v[212:213], 0, s[70:71]
	s_mov_b32 m0, s46
	s_nop 0
	global_load_lds_dwordx4 v[148:149], off
	v_lshl_add_u64 v[148:149], v[214:215], 0, s[70:71]
	s_mov_b32 m0, s47
	s_nop 0
	global_load_lds_dwordx4 v[148:149], off
	s_waitcnt vmcnt(8)
	s_waitcnt lgkmcnt(0)
	s_barrier
	s_setprio 1
	v_mfma_f32_16x16x32_bf16 v[62:65], v[140:143], v[180:183], v[62:65]
	v_mfma_f32_16x16x32_bf16 v[58:61], v[156:159], v[180:183], v[58:61]
	v_mfma_f32_16x16x32_bf16 v[54:57], v[140:143], v[188:191], v[54:57]
	v_mfma_f32_16x16x32_bf16 v[50:53], v[156:159], v[188:191], v[50:53]
	v_mfma_f32_16x16x32_bf16 v[38:41], v[140:143], v[196:199], v[38:41]
	v_mfma_f32_16x16x32_bf16 v[34:37], v[156:159], v[196:199], v[34:37]
	v_mfma_f32_16x16x32_bf16 v[22:25], v[140:143], v[204:207], v[22:25]
	v_mfma_f32_16x16x32_bf16 v[18:21], v[156:159], v[204:207], v[18:21]
	v_mfma_f32_16x16x32_bf16 v[62:65], v[144:147], v[184:187], v[62:65]
	v_mfma_f32_16x16x32_bf16 v[58:61], v[160:163], v[184:187], v[58:61]
	v_mfma_f32_16x16x32_bf16 v[54:57], v[144:147], v[192:195], v[54:57]
	v_mfma_f32_16x16x32_bf16 v[50:53], v[160:163], v[192:195], v[50:53]
	v_mfma_f32_16x16x32_bf16 v[38:41], v[144:147], v[200:203], v[38:41]
	v_mfma_f32_16x16x32_bf16 v[34:37], v[160:163], v[200:203], v[34:37]
	v_mfma_f32_16x16x32_bf16 v[22:25], v[144:147], v[208:211], v[22:25]
	v_mfma_f32_16x16x32_bf16 v[18:21], v[160:163], v[208:211], v[18:21]
	v_mfma_f32_16x16x32_bf16 v[46:49], v[164:167], v[180:183], v[46:49]
	v_mfma_f32_16x16x32_bf16 v[42:45], v[172:175], v[180:183], v[42:45]
	v_mfma_f32_16x16x32_bf16 v[30:33], v[164:167], v[188:191], v[30:33]
	v_mfma_f32_16x16x32_bf16 v[26:29], v[172:175], v[188:191], v[26:29]
	v_mfma_f32_16x16x32_bf16 v[14:17], v[164:167], v[196:199], v[14:17]
	v_mfma_f32_16x16x32_bf16 v[10:13], v[172:175], v[196:199], v[10:13]
	v_mfma_f32_16x16x32_bf16 v[6:9], v[164:167], v[204:207], v[6:9]
	v_mfma_f32_16x16x32_bf16 v[2:5], v[172:175], v[204:207], v[2:5]
	v_mfma_f32_16x16x32_bf16 v[46:49], v[168:171], v[184:187], v[46:49]
	v_mfma_f32_16x16x32_bf16 v[42:45], v[176:179], v[184:187], v[42:45]
	v_mfma_f32_16x16x32_bf16 v[30:33], v[168:171], v[192:195], v[30:33]
	v_mfma_f32_16x16x32_bf16 v[26:29], v[176:179], v[192:195], v[26:29]
	v_mfma_f32_16x16x32_bf16 v[14:17], v[168:171], v[200:203], v[14:17]
	v_mfma_f32_16x16x32_bf16 v[10:13], v[176:179], v[200:203], v[10:13]
	v_mfma_f32_16x16x32_bf16 v[6:9], v[168:171], v[208:211], v[6:9]
	v_mfma_f32_16x16x32_bf16 v[2:5], v[176:179], v[208:211], v[2:5]
	s_setprio 0
	s_barrier
	s_movk_i32 s9, 0x100
	s_andn2_b64 vcc, exec, s[4:5]
	s_mov_b64 s[38:39], -1
	s_mov_b64 s[4:5], 0
	s_cbranch_vccz .LBB0_376
	s_and_b64 vcc, exec, s[14:15]
	s_cbranch_vccz .LBB0_379
	s_barrier

.LBB0_393:
	s_ashr_i32 s19, s18, 31
	s_lshl_b64 s[24:25], s[18:19], 16
	s_add_u32 s24, s29, s24
	s_addc_u32 s25, s38, s25
	s_and_b64 s[4:5], s[4:5], exec
	s_cselect_b32 s5, s25, s27
	s_cselect_b32 s4, s24, s26
	s_add_i32 s19, 0, 0x10000
	s_add_i32 s48, 0, 0x14000
	v_add_u32_e32 v14, s19, v137
	v_add_u32_e32 v30, s48, v137
	.p2align 6
	ds_read_b128 v[2:5], v14
	ds_read_b128 v[6:9], v14 offset:1024
	ds_read_b128 v[10:13], v14 offset:2048
	ds_read_b128 v[14:17], v14 offset:3072
	ds_read_b128 v[18:21], v30
	ds_read_b128 v[22:25], v30 offset:1024
	ds_read_b128 v[26:29], v30 offset:2048
	ds_read_b128 v[30:33], v30 offset:3072
	s_add_u32 s26, s36, 0x58080
	s_addc_u32 s27, s37, 0
	v_lshl_add_u64 v[66:67], s[26:27], 0, v[134:135]
	s_add_i32 m0, s40, 0xc000
	ds_read_b128 v[34:37], v139
	ds_read_b128 v[38:41], v139 offset:1024
	ds_read_b128 v[42:45], v139 offset:2048
	ds_read_b128 v[46:49], v139 offset:3072
	ds_read_b128 v[50:53], v139 offset:4096
	ds_read_b128 v[54:57], v139 offset:5120
	ds_read_b128 v[58:61], v139 offset:6144
	ds_read_b128 v[62:65], v139 offset:7168
	global_load_lds_dwordx4 v[66:67], off
	v_lshl_add_u64 v[66:67], s[26:27], 0, v[132:133]
	s_add_i32 m0, s40, 0xe000
	s_nop 0
	global_load_lds_dwordx4 v[66:67], off
	s_waitcnt vmcnt(8)
	s_waitcnt lgkmcnt(0)
	s_barrier
	s_setprio 1
	v_mfma_f32_16x16x32_bf16 v[66:69], v[2:5], v[34:37], 0
	v_mfma_f32_16x16x32_bf16 v[70:73], v[10:13], v[34:37], 0
	v_mfma_f32_16x16x32_bf16 v[74:77], v[2:5], v[42:45], 0
	v_mfma_f32_16x16x32_bf16 v[78:81], v[10:13], v[42:45], 0
	v_mfma_f32_16x16x32_bf16 v[82:85], v[2:5], v[50:53], 0
	v_mfma_f32_16x16x32_bf16 v[86:89], v[10:13], v[50:53], 0
	v_mfma_f32_16x16x32_bf16 v[90:93], v[2:5], v[58:61], 0
	v_mfma_f32_16x16x32_bf16 v[94:97], v[10:13], v[58:61], 0
	v_mfma_f32_16x16x32_bf16 v[66:69], v[6:9], v[38:41], v[66:69]
	v_mfma_f32_16x16x32_bf16 v[70:73], v[14:17], v[38:41], v[70:73]
	v_mfma_f32_16x16x32_bf16 v[74:77], v[6:9], v[46:49], v[74:77]
	v_mfma_f32_16x16x32_bf16 v[78:81], v[14:17], v[46:49], v[78:81]
	v_mfma_f32_16x16x32_bf16 v[82:85], v[6:9], v[54:57], v[82:85]
	v_mfma_f32_16x16x32_bf16 v[86:89], v[14:17], v[54:57], v[86:89]
	v_mfma_f32_16x16x32_bf16 v[90:93], v[6:9], v[62:65], v[90:93]
	v_mfma_f32_16x16x32_bf16 v[94:97], v[14:17], v[62:65], v[94:97]
	v_mfma_f32_16x16x32_bf16 v[98:101], v[18:21], v[34:37], 0
	v_mfma_f32_16x16x32_bf16 v[34:37], v[26:29], v[34:37], 0
	v_mfma_f32_16x16x32_bf16 v[98:101], v[22:25], v[38:41], v[98:101]
	v_mfma_f32_16x16x32_bf16 v[34:37], v[30:33], v[38:41], v[34:37]
	v_mfma_f32_16x16x32_bf16 v[38:41], v[18:21], v[42:45], 0
	v_mfma_f32_16x16x32_bf16 v[42:45], v[26:29], v[42:45], 0
	v_mfma_f32_16x16x32_bf16 v[102:105], v[30:33], v[46:49], v[42:45]
	v_mfma_f32_16x16x32_bf16 v[42:45], v[18:21], v[50:53], 0
	v_mfma_f32_16x16x32_bf16 v[114:117], v[22:25], v[54:57], v[42:45]
	v_mfma_f32_16x16x32_bf16 v[42:45], v[26:29], v[50:53], 0
	v_mfma_f32_16x16x32_bf16 v[50:53], v[30:33], v[54:57], v[42:45]
	v_mfma_f32_16x16x32_bf16 v[42:45], v[18:21], v[58:61], 0
	v_mfma_f32_16x16x32_bf16 v[54:57], v[22:25], v[62:65], v[42:45]
	v_mfma_f32_16x16x32_bf16 v[42:45], v[26:29], v[58:61], 0
	v_mfma_f32_16x16x32_bf16 v[38:41], v[22:25], v[46:49], v[38:41]
	v_mfma_f32_16x16x32_bf16 v[58:61], v[30:33], v[62:65], v[42:45]
	s_setprio 0
	s_barrier
	s_add_i32 s19, s19, s39
	v_lshl_add_u64 v[148:149], s[4:5], 0, v[0:1]
	s_mov_b32 m0, s19
	s_nop 0
	ds_read_b128 v[42:45], v139 offset:16384
	ds_read_b128 v[46:49], v139 offset:17408
	ds_read_b128 v[62:65], v139 offset:18432
	ds_read_b128 v[106:109], v139 offset:19456
	ds_read_b128 v[110:113], v139 offset:20480
	ds_read_b128 v[118:121], v139 offset:21504
	ds_read_b128 v[122:125], v139 offset:22528
	ds_read_b128 v[126:129], v139 offset:23552
	global_load_lds_dwordx4 v[148:149], off
	s_add_i32 m0, s19, 0x2000
	s_add_u32 s26, s4, 0x8000
	v_lshl_add_u64 v[150:151], s[4:5], 0, v[130:131]
	s_addc_u32 s27, s5, 0
	s_add_i32 s19, s48, s39
	global_load_lds_dwordx4 v[150:151], off
	v_lshl_add_u64 v[140:141], s[26:27], 0, v[0:1]
	s_mov_b32 m0, s19
	v_lshl_add_u64 v[252:253], s[22:23], 0, v[134:135]
	global_load_lds_dwordx4 v[140:141], off
	v_lshl_add_u64 v[140:141], s[26:27], 0, v[130:131]
	s_add_i32 m0, s19, 0x2000
	v_lshl_add_u64 v[242:243], s[22:23], 0, v[132:133]
	global_load_lds_dwordx4 v[140:141], off
	s_mov_b32 m0, s40
	s_nop 0
	global_load_lds_dwordx4 v[252:253], off
	s_mov_b32 m0, s41
	s_nop 0
	global_load_lds_dwordx4 v[242:243], off
	s_waitcnt vmcnt(8)
	s_waitcnt lgkmcnt(0)
	s_barrier
	s_setprio 1
	v_mfma_f32_16x16x32_bf16 v[140:143], v[2:5], v[42:45], 0
	v_mfma_f32_16x16x32_bf16 v[156:159], v[2:5], v[62:65], 0
	v_mfma_f32_16x16x32_bf16 v[164:167], v[2:5], v[110:113], 0
	v_mfma_f32_16x16x32_bf16 v[2:5], v[2:5], v[122:125], 0
	v_mfma_f32_16x16x32_bf16 v[140:143], v[6:9], v[46:49], v[140:143]
	v_mfma_f32_16x16x32_bf16 v[156:159], v[6:9], v[106:109], v[156:159]
	v_mfma_f32_16x16x32_bf16 v[164:167], v[6:9], v[118:121], v[164:167]
	v_mfma_f32_16x16x32_bf16 v[2:5], v[6:9], v[126:129], v[2:5]
	v_mfma_f32_16x16x32_bf16 v[6:9], v[10:13], v[122:125], 0
	v_mfma_f32_16x16x32_bf16 v[144:147], v[10:13], v[42:45], 0
	v_mfma_f32_16x16x32_bf16 v[160:163], v[10:13], v[62:65], 0
	v_mfma_f32_16x16x32_bf16 v[168:171], v[10:13], v[110:113], 0
	v_mfma_f32_16x16x32_bf16 v[6:9], v[14:17], v[126:129], v[6:9]
	v_mfma_f32_16x16x32_bf16 v[144:147], v[14:17], v[46:49], v[144:147]
	v_mfma_f32_16x16x32_bf16 v[160:163], v[14:17], v[106:109], v[160:163]
	v_mfma_f32_16x16x32_bf16 v[168:171], v[14:17], v[118:121], v[168:171]
	v_mfma_f32_16x16x32_bf16 v[10:13], v[18:21], v[42:45], 0
	v_mfma_f32_16x16x32_bf16 v[172:175], v[22:25], v[46:49], v[10:13]
	v_mfma_f32_16x16x32_bf16 v[10:13], v[26:29], v[42:45], 0
	v_mfma_f32_16x16x32_bf16 v[176:179], v[30:33], v[46:49], v[10:13]
	v_mfma_f32_16x16x32_bf16 v[10:13], v[18:21], v[62:65], 0
	v_mfma_f32_16x16x32_bf16 v[180:183], v[22:25], v[106:109], v[10:13]
	v_mfma_f32_16x16x32_bf16 v[10:13], v[26:29], v[62:65], 0
	v_mfma_f32_16x16x32_bf16 v[184:187], v[30:33], v[106:109], v[10:13]
	v_mfma_f32_16x16x32_bf16 v[10:13], v[18:21], v[110:113], 0
	v_mfma_f32_16x16x32_bf16 v[188:191], v[22:25], v[118:121], v[10:13]
	v_mfma_f32_16x16x32_bf16 v[10:13], v[26:29], v[110:113], 0
	v_mfma_f32_16x16x32_bf16 v[192:195], v[30:33], v[118:121], v[10:13]
	v_mfma_f32_16x16x32_bf16 v[10:13], v[18:21], v[122:125], 0
	v_mfma_f32_16x16x32_bf16 v[18:21], v[22:25], v[126:129], v[10:13]
	v_mfma_f32_16x16x32_bf16 v[10:13], v[26:29], v[122:125], 0
	v_mfma_f32_16x16x32_bf16 v[22:25], v[30:33], v[126:129], v[10:13]
	s_setprio 0
	s_barrier
	s_add_i32 s19, 0, 0x18000
	s_nop 3
	v_add_u32_e32 v10, s19, v137
	s_add_i32 s36, 0, 0x1c000
	ds_read_b128 v[118:121], v10
	ds_read_b128 v[196:199], v10 offset:1024
	ds_read_b128 v[200:203], v10 offset:2048
	ds_read_b128 v[204:207], v10 offset:3072
	v_add_u32_e32 v10, s36, v137
	ds_read_b128 v[208:211], v10
	ds_read_b128 v[212:215], v10 offset:1024
	ds_read_b128 v[216:219], v10 offset:2048
	ds_read_b128 v[220:223], v10 offset:3072
	s_add_u32 s26, s22, 0x58000
	s_addc_u32 s27, s23, 0
	s_mov_b32 m0, s42
	v_lshl_add_u64 v[10:11], s[26:27], 0, v[134:135]
	ds_read_b128 v[26:29], v139 offset:32768
	ds_read_b128 v[30:33], v139 offset:33792
	ds_read_b128 v[62:65], v139 offset:34816
	ds_read_b128 v[224:227], v139 offset:35840
	ds_read_b128 v[228:231], v139 offset:36864
	ds_read_b128 v[232:235], v139 offset:37888
	ds_read_b128 v[236:239], v139 offset:38912
	ds_read_b128 v[248:251], v139 offset:39936
	global_load_lds_dwordx4 v[10:11], off
	v_lshl_add_u64 v[10:11], s[26:27], 0, v[132:133]
	s_mov_b32 m0, s43
	s_nop 0
	global_load_lds_dwordx4 v[10:11], off
	s_waitcnt vmcnt(8)
	s_waitcnt lgkmcnt(0)
	s_barrier
	s_setprio 1
	v_mfma_f32_16x16x32_bf16 v[10:13], v[118:121], v[26:29], v[66:69]
	v_mfma_f32_16x16x32_bf16 v[106:109], v[196:199], v[30:33], v[10:13]
	v_mfma_f32_16x16x32_bf16 v[10:13], v[200:203], v[26:29], v[70:73]
	v_mfma_f32_16x16x32_bf16 v[110:113], v[204:207], v[30:33], v[10:13]
	v_mfma_f32_16x16x32_bf16 v[10:13], v[118:121], v[62:65], v[74:77]
	v_mfma_f32_16x16x32_bf16 v[74:77], v[196:199], v[224:227], v[10:13]
	v_mfma_f32_16x16x32_bf16 v[10:13], v[200:203], v[62:65], v[78:81]
	v_mfma_f32_16x16x32_bf16 v[78:81], v[204:207], v[224:227], v[10:13]
	v_mfma_f32_16x16x32_bf16 v[10:13], v[118:121], v[228:231], v[82:85]
	v_mfma_f32_16x16x32_bf16 v[42:45], v[196:199], v[232:235], v[10:13]
	v_mfma_f32_16x16x32_bf16 v[10:13], v[200:203], v[228:231], v[86:89]
	v_mfma_f32_16x16x32_bf16 v[46:49], v[204:207], v[232:235], v[10:13]
	v_mfma_f32_16x16x32_bf16 v[10:13], v[118:121], v[236:239], v[90:93]
	v_mfma_f32_16x16x32_bf16 v[14:17], v[200:203], v[236:239], v[94:97]
	v_mfma_f32_16x16x32_bf16 v[10:13], v[196:199], v[248:251], v[10:13]
	v_mfma_f32_16x16x32_bf16 v[14:17], v[204:207], v[248:251], v[14:17]
	v_mfma_f32_16x16x32_bf16 v[66:69], v[208:211], v[26:29], v[98:101]
	v_mfma_f32_16x16x32_bf16 v[26:29], v[216:219], v[26:29], v[34:37]
	v_mfma_f32_16x16x32_bf16 v[126:129], v[220:223], v[30:33], v[26:29]
	v_mfma_f32_16x16x32_bf16 v[26:29], v[208:211], v[62:65], v[38:41]
	v_mfma_f32_16x16x32_bf16 v[98:101], v[212:215], v[224:227], v[26:29]
	v_mfma_f32_16x16x32_bf16 v[26:29], v[216:219], v[62:65], v[102:105]
	v_mfma_f32_16x16x32_bf16 v[102:105], v[220:223], v[224:227], v[26:29]
	v_mfma_f32_16x16x32_bf16 v[26:29], v[208:211], v[228:231], v[114:117]
	v_mfma_f32_16x16x32_bf16 v[122:125], v[212:215], v[30:33], v[66:69]
	v_mfma_f32_16x16x32_bf16 v[66:69], v[212:215], v[232:235], v[26:29]
	v_mfma_f32_16x16x32_bf16 v[26:29], v[216:219], v[228:231], v[50:53]
	v_mfma_f32_16x16x32_bf16 v[70:73], v[220:223], v[232:235], v[26:29]
	v_mfma_f32_16x16x32_bf16 v[26:29], v[208:211], v[236:239], v[54:57]
	v_mfma_f32_16x16x32_bf16 v[34:37], v[212:215], v[248:251], v[26:29]
	v_mfma_f32_16x16x32_bf16 v[26:29], v[216:219], v[236:239], v[58:61]
	v_mfma_f32_16x16x32_bf16 v[38:41], v[220:223], v[248:251], v[26:29]
	s_setprio 0
	s_barrier
	s_add_i32 s19, s19, s39
	s_nop 3
	v_lshl_add_u64 v[26:27], v[148:149], 0, s[70:71]
	s_mov_b32 m0, s19
	ds_read_b128 v[50:53], v139 offset:49152
	ds_read_b128 v[54:57], v139 offset:50176
	ds_read_b128 v[86:89], v139 offset:51200
	ds_read_b128 v[224:227], v139 offset:52224
	ds_read_b128 v[228:231], v139 offset:53248
	ds_read_b128 v[232:235], v139 offset:54272
	ds_read_b128 v[236:239], v139 offset:55296
	ds_read_b128 v[248:251], v139 offset:56320
	global_load_lds_dwordx4 v[26:27], off
	s_add_i32 m0, s19, 0x2000
	s_add_u32 s4, s4, 0x8080
	v_lshl_add_u64 v[26:27], v[150:151], 0, s[70:71]
	s_addc_u32 s5, s5, 0
	s_add_i32 s19, s36, s39
	global_load_lds_dwordx4 v[26:27], off
	v_lshl_add_u64 v[26:27], s[4:5], 0, v[0:1]
	s_mov_b32 m0, s19
	s_nop 0
	global_load_lds_dwordx4 v[26:27], off
	v_lshl_add_u64 v[26:27], s[4:5], 0, v[130:131]
	s_add_i32 m0, s19, 0x2000
	s_nop 0
	global_load_lds_dwordx4 v[26:27], off
	v_lshl_add_u64 v[26:27], v[252:253], 0, s[70:71]
	s_mov_b32 m0, s44
	s_nop 0
	global_load_lds_dwordx4 v[26:27], off
	v_lshl_add_u64 v[26:27], v[242:243], 0, s[70:71]
	s_mov_b32 m0, s45
	s_nop 0
	global_load_lds_dwordx4 v[26:27], off
	s_waitcnt vmcnt(8)
	s_waitcnt lgkmcnt(0)
	s_barrier
	s_setprio 1
	v_mfma_f32_16x16x32_bf16 v[26:29], v[118:121], v[50:53], v[140:143]
	v_mfma_f32_16x16x32_bf16 v[90:93], v[196:199], v[54:57], v[26:29]
	v_mfma_f32_16x16x32_bf16 v[26:29], v[200:203], v[50:53], v[144:147]
	v_mfma_f32_16x16x32_bf16 v[94:97], v[204:207], v[54:57], v[26:29]
	v_mfma_f32_16x16x32_bf16 v[26:29], v[118:121], v[86:89], v[156:159]
	v_mfma_f32_16x16x32_bf16 v[58:61], v[196:199], v[224:227], v[26:29]
	v_mfma_f32_16x16x32_bf16 v[26:29], v[200:203], v[86:89], v[160:163]
	v_mfma_f32_16x16x32_bf16 v[62:65], v[204:207], v[224:227], v[26:29]
	v_mfma_f32_16x16x32_bf16 v[26:29], v[118:121], v[228:231], v[164:167]
	v_mfma_f32_16x16x32_bf16 v[30:33], v[200:203], v[228:231], v[168:171]
	v_mfma_f32_16x16x32_bf16 v[2:5], v[118:121], v[236:239], v[2:5]
	v_mfma_f32_16x16x32_bf16 v[6:9], v[200:203], v[236:239], v[6:9]
	v_mfma_f32_16x16x32_bf16 v[26:29], v[196:199], v[232:235], v[26:29]
	v_mfma_f32_16x16x32_bf16 v[30:33], v[204:207], v[232:235], v[30:33]
	v_mfma_f32_16x16x32_bf16 v[2:5], v[196:199], v[248:251], v[2:5]
	v_mfma_f32_16x16x32_bf16 v[6:9], v[204:207], v[248:251], v[6:9]
	v_mfma_f32_16x16x32_bf16 v[82:85], v[208:211], v[50:53], v[172:175]
	v_mfma_f32_16x16x32_bf16 v[50:53], v[216:219], v[50:53], v[176:179]
	v_mfma_f32_16x16x32_bf16 v[118:121], v[220:223], v[54:57], v[50:53]
	v_mfma_f32_16x16x32_bf16 v[50:53], v[208:211], v[86:89], v[180:183]
	v_mfma_f32_16x16x32_bf16 v[114:117], v[212:215], v[54:57], v[82:85]
	v_mfma_f32_16x16x32_bf16 v[82:85], v[212:215], v[224:227], v[50:53]
	v_mfma_f32_16x16x32_bf16 v[50:53], v[216:219], v[86:89], v[184:187]
	v_mfma_f32_16x16x32_bf16 v[86:89], v[220:223], v[224:227], v[50:53]
	v_mfma_f32_16x16x32_bf16 v[50:53], v[208:211], v[228:231], v[188:191]
	v_mfma_f32_16x16x32_bf16 v[54:57], v[216:219], v[228:231], v[192:195]
	v_mfma_f32_16x16x32_bf16 v[18:21], v[208:211], v[236:239], v[18:21]
	v_mfma_f32_16x16x32_bf16 v[22:25], v[216:219], v[236:239], v[22:25]
	v_mfma_f32_16x16x32_bf16 v[50:53], v[212:215], v[232:235], v[50:53]
	v_mfma_f32_16x16x32_bf16 v[54:57], v[220:223], v[232:235], v[54:57]
	v_mfma_f32_16x16x32_bf16 v[18:21], v[212:215], v[248:251], v[18:21]
	v_mfma_f32_16x16x32_bf16 v[22:25], v[220:223], v[248:251], v[22:25]
	s_setprio 0
	s_barrier
	s_andn2_b64 vcc, exec, s[14:15]
	s_cbranch_vccnz .LBB0_395
	s_barrier

.LBB0_701:
	s_add_i32 s75, s26, 2
	s_add_u32 s9, s60, 0xfffc0080
	s_addc_u32 s27, s61, -1
	s_add_i32 s78, 0, 0x10000
	s_cmp_eq_u32 s19, s26
	s_cselect_b32 s73, s23, s27
	s_cselect_b32 s72, s22, s9
	s_cselect_b32 s27, s25, s29
	s_cselect_b32 s26, s24, s28
	s_add_i32 s9, 0, 0x14000
	s_waitcnt vmcnt(0)
	v_add_u32_e32 v142, s78, v177
	v_add_u32_e32 v148, s9, v177
	ds_read_b128 v[130:133], v142
	ds_read_b128 v[134:137], v142 offset:1024
	ds_read_b128 v[138:141], v142 offset:2048
	ds_read_b128 v[142:145], v142 offset:3072
	ds_read_b128 v[164:167], v148
	ds_read_b128 v[168:171], v148 offset:1024
	ds_read_b128 v[172:175], v148 offset:2048
	ds_read_b128 v[180:183], v148 offset:3072
	v_lshl_add_u64 v[148:149], s[60:61], 0, v[160:161]
	s_add_i32 m0, s37, 0xc000
	ds_read_b128 v[184:187], v179
	ds_read_b128 v[188:191], v179 offset:1024
	ds_read_b128 v[192:195], v179 offset:2048
	ds_read_b128 v[196:199], v179 offset:3072
	ds_read_b128 v[200:203], v179 offset:4096
	ds_read_b128 v[204:207], v179 offset:5120
	ds_read_b128 v[208:211], v179 offset:6144
	ds_read_b128 v[212:215], v179 offset:7168
	global_load_lds_dwordx4 v[148:149], off
	v_lshl_add_u64 v[148:149], s[60:61], 0, v[162:163]
	s_add_i32 m0, s37, 0xe000
	s_nop 0
	global_load_lds_dwordx4 v[148:149], off
	s_waitcnt vmcnt(8)
	s_waitcnt lgkmcnt(0)
	s_barrier
	s_setprio 1
	v_mfma_f32_16x16x32_bf16 v[126:129], v[130:133], v[184:187], v[126:129]
	v_mfma_f32_16x16x32_bf16 v[122:125], v[138:141], v[184:187], v[122:125]
	v_mfma_f32_16x16x32_bf16 v[110:113], v[130:133], v[192:195], v[110:113]
	v_mfma_f32_16x16x32_bf16 v[106:109], v[138:141], v[192:195], v[106:109]
	v_mfma_f32_16x16x32_bf16 v[94:97], v[130:133], v[200:203], v[94:97]
	v_mfma_f32_16x16x32_bf16 v[90:93], v[138:141], v[200:203], v[90:93]
	v_mfma_f32_16x16x32_bf16 v[78:81], v[130:133], v[208:211], v[78:81]
	v_mfma_f32_16x16x32_bf16 v[74:77], v[138:141], v[208:211], v[74:77]
	v_mfma_f32_16x16x32_bf16 v[126:129], v[134:137], v[188:191], v[126:129]
	v_mfma_f32_16x16x32_bf16 v[122:125], v[142:145], v[188:191], v[122:125]
	v_mfma_f32_16x16x32_bf16 v[110:113], v[134:137], v[196:199], v[110:113]
	v_mfma_f32_16x16x32_bf16 v[106:109], v[142:145], v[196:199], v[106:109]
	v_mfma_f32_16x16x32_bf16 v[94:97], v[134:137], v[204:207], v[94:97]
	v_mfma_f32_16x16x32_bf16 v[90:93], v[142:145], v[204:207], v[90:93]
	v_mfma_f32_16x16x32_bf16 v[78:81], v[134:137], v[212:215], v[78:81]
	v_mfma_f32_16x16x32_bf16 v[74:77], v[142:145], v[212:215], v[74:77]
	v_mfma_f32_16x16x32_bf16 v[118:121], v[164:167], v[184:187], v[118:121]
	v_mfma_f32_16x16x32_bf16 v[114:117], v[172:175], v[184:187], v[114:117]
	v_mfma_f32_16x16x32_bf16 v[102:105], v[164:167], v[192:195], v[102:105]
	v_mfma_f32_16x16x32_bf16 v[98:101], v[172:175], v[192:195], v[98:101]
	v_mfma_f32_16x16x32_bf16 v[86:89], v[164:167], v[200:203], v[86:89]
	v_mfma_f32_16x16x32_bf16 v[82:85], v[172:175], v[200:203], v[82:85]
	v_mfma_f32_16x16x32_bf16 v[70:73], v[164:167], v[208:211], v[70:73]
	v_mfma_f32_16x16x32_bf16 v[66:69], v[172:175], v[208:211], v[66:69]
	v_mfma_f32_16x16x32_bf16 v[118:121], v[168:171], v[188:191], v[118:121]
	v_mfma_f32_16x16x32_bf16 v[114:117], v[180:183], v[188:191], v[114:117]
	v_mfma_f32_16x16x32_bf16 v[102:105], v[168:171], v[196:199], v[102:105]
	v_mfma_f32_16x16x32_bf16 v[98:101], v[180:183], v[196:199], v[98:101]
	v_mfma_f32_16x16x32_bf16 v[86:89], v[168:171], v[204:207], v[86:89]
	v_mfma_f32_16x16x32_bf16 v[82:85], v[180:183], v[204:207], v[82:85]
	v_mfma_f32_16x16x32_bf16 v[70:73], v[168:171], v[212:215], v[70:73]
	v_mfma_f32_16x16x32_bf16 v[66:69], v[180:183], v[212:215], v[66:69]
	s_setprio 0
	s_barrier
	s_add_i32 s78, s78, s41
	v_lshl_add_u64 v[148:149], s[26:27], 0, v[0:1]
	s_mov_b32 m0, s78
	ds_read_b128 v[184:187], v179 offset:16384
	ds_read_b128 v[188:191], v179 offset:17408
	ds_read_b128 v[192:195], v179 offset:18432
	ds_read_b128 v[196:199], v179 offset:19456
	ds_read_b128 v[200:203], v179 offset:20480
	ds_read_b128 v[204:207], v179 offset:21504
	ds_read_b128 v[208:211], v179 offset:22528
	ds_read_b128 v[212:215], v179 offset:23552
	global_load_lds_dwordx4 v[148:149], off
	s_add_i32 m0, s78, 0x2000
	s_add_u32 s78, s26, 0x40000
	v_lshl_add_u64 v[150:151], s[26:27], 0, v[158:159]
	s_addc_u32 s79, s27, 0
	s_add_i32 s9, s9, s41
	global_load_lds_dwordx4 v[150:151], off
	v_lshl_add_u64 v[216:217], s[78:79], 0, v[0:1]
	s_mov_b32 m0, s9
	v_lshl_add_u64 v[218:219], s[72:73], 0, v[156:157]
	global_load_lds_dwordx4 v[216:217], off
	v_lshl_add_u64 v[216:217], s[78:79], 0, v[158:159]
	s_add_i32 m0, s9, 0x2000
	s_nop 0
	global_load_lds_dwordx4 v[216:217], off
	v_lshl_add_u64 v[216:217], s[72:73], 0, v[146:147]
	s_mov_b32 m0, s37
	s_nop 0
	global_load_lds_dwordx4 v[216:217], off
	s_mov_b32 m0, s39
	s_nop 0
	global_load_lds_dwordx4 v[218:219], off
	s_waitcnt vmcnt(8)
	s_waitcnt lgkmcnt(0)
	s_barrier
	s_setprio 1
	v_mfma_f32_16x16x32_bf16 v[62:65], v[130:133], v[184:187], v[62:65]
	v_mfma_f32_16x16x32_bf16 v[58:61], v[138:141], v[184:187], v[58:61]
	v_mfma_f32_16x16x32_bf16 v[46:49], v[130:133], v[192:195], v[46:49]
	v_mfma_f32_16x16x32_bf16 v[42:45], v[138:141], v[192:195], v[42:45]
	v_mfma_f32_16x16x32_bf16 v[30:33], v[130:133], v[200:203], v[30:33]
	v_mfma_f32_16x16x32_bf16 v[26:29], v[138:141], v[200:203], v[26:29]
	v_mfma_f32_16x16x32_bf16 v[14:17], v[130:133], v[208:211], v[14:17]
	v_mfma_f32_16x16x32_bf16 v[10:13], v[138:141], v[208:211], v[10:13]
	v_mfma_f32_16x16x32_bf16 v[62:65], v[134:137], v[188:191], v[62:65]
	v_mfma_f32_16x16x32_bf16 v[58:61], v[142:145], v[188:191], v[58:61]
	v_mfma_f32_16x16x32_bf16 v[46:49], v[134:137], v[196:199], v[46:49]
	v_mfma_f32_16x16x32_bf16 v[42:45], v[142:145], v[196:199], v[42:45]
	v_mfma_f32_16x16x32_bf16 v[30:33], v[134:137], v[204:207], v[30:33]
	v_mfma_f32_16x16x32_bf16 v[26:29], v[142:145], v[204:207], v[26:29]
	v_mfma_f32_16x16x32_bf16 v[14:17], v[134:137], v[212:215], v[14:17]
	v_mfma_f32_16x16x32_bf16 v[10:13], v[142:145], v[212:215], v[10:13]
	v_mfma_f32_16x16x32_bf16 v[54:57], v[164:167], v[184:187], v[54:57]
	v_mfma_f32_16x16x32_bf16 v[50:53], v[172:175], v[184:187], v[50:53]
	v_mfma_f32_16x16x32_bf16 v[38:41], v[164:167], v[192:195], v[38:41]
	v_mfma_f32_16x16x32_bf16 v[34:37], v[172:175], v[192:195], v[34:37]
	v_mfma_f32_16x16x32_bf16 v[22:25], v[164:167], v[200:203], v[22:25]
	v_mfma_f32_16x16x32_bf16 v[18:21], v[172:175], v[200:203], v[18:21]
	v_mfma_f32_16x16x32_bf16 v[6:9], v[164:167], v[208:211], v[6:9]
	v_mfma_f32_16x16x32_bf16 v[2:5], v[172:175], v[208:211], v[2:5]
	v_mfma_f32_16x16x32_bf16 v[54:57], v[168:171], v[188:191], v[54:57]
	v_mfma_f32_16x16x32_bf16 v[50:53], v[180:183], v[188:191], v[50:53]
	v_mfma_f32_16x16x32_bf16 v[38:41], v[168:171], v[196:199], v[38:41]
	v_mfma_f32_16x16x32_bf16 v[34:37], v[180:183], v[196:199], v[34:37]
	v_mfma_f32_16x16x32_bf16 v[22:25], v[168:171], v[204:207], v[22:25]
	v_mfma_f32_16x16x32_bf16 v[18:21], v[180:183], v[204:207], v[18:21]
	v_mfma_f32_16x16x32_bf16 v[6:9], v[168:171], v[212:215], v[6:9]
	v_mfma_f32_16x16x32_bf16 v[2:5], v[180:183], v[212:215], v[2:5]
	s_setprio 0
	s_barrier
	s_add_i32 s9, 0, 0x18000
	s_add_i32 s78, 0, 0x1c000
	v_add_u32_e32 v142, s9, v177
	v_add_u32_e32 v180, s78, v177
	ds_read_b128 v[130:133], v142
	ds_read_b128 v[134:137], v142 offset:1024
	ds_read_b128 v[138:141], v142 offset:2048
	ds_read_b128 v[142:145], v142 offset:3072
	ds_read_b128 v[164:167], v180
	ds_read_b128 v[168:171], v180 offset:1024
	ds_read_b128 v[172:175], v180 offset:2048
	ds_read_b128 v[180:183], v180 offset:3072
	s_add_u32 s72, s72, 0x40000
	s_addc_u32 s73, s73, 0
	s_mov_b32 m0, s44
	v_lshl_add_u64 v[220:221], s[72:73], 0, v[146:147]
	ds_read_b128 v[184:187], v179 offset:32768
	ds_read_b128 v[188:191], v179 offset:33792
	ds_read_b128 v[192:195], v179 offset:34816
	ds_read_b128 v[196:199], v179 offset:35840
	ds_read_b128 v[200:203], v179 offset:36864
	ds_read_b128 v[204:207], v179 offset:37888
	ds_read_b128 v[208:211], v179 offset:38912
	ds_read_b128 v[212:215], v179 offset:39936
	global_load_lds_dwordx4 v[220:221], off
	v_lshl_add_u64 v[220:221], s[72:73], 0, v[156:157]
	s_mov_b32 m0, s45
	s_nop 0
	global_load_lds_dwordx4 v[220:221], off
	s_waitcnt vmcnt(8)
	s_waitcnt lgkmcnt(0)
	s_barrier
	s_setprio 1
	v_mfma_f32_16x16x32_bf16 v[126:129], v[130:133], v[184:187], v[126:129]
	v_mfma_f32_16x16x32_bf16 v[122:125], v[138:141], v[184:187], v[122:125]
	v_mfma_f32_16x16x32_bf16 v[110:113], v[130:133], v[192:195], v[110:113]
	v_mfma_f32_16x16x32_bf16 v[106:109], v[138:141], v[192:195], v[106:109]
	v_mfma_f32_16x16x32_bf16 v[94:97], v[130:133], v[200:203], v[94:97]
	v_mfma_f32_16x16x32_bf16 v[90:93], v[138:141], v[200:203], v[90:93]
	v_mfma_f32_16x16x32_bf16 v[78:81], v[130:133], v[208:211], v[78:81]
	v_mfma_f32_16x16x32_bf16 v[74:77], v[138:141], v[208:211], v[74:77]
	v_mfma_f32_16x16x32_bf16 v[126:129], v[134:137], v[188:191], v[126:129]
	v_mfma_f32_16x16x32_bf16 v[122:125], v[142:145], v[188:191], v[122:125]
	v_mfma_f32_16x16x32_bf16 v[110:113], v[134:137], v[196:199], v[110:113]
	v_mfma_f32_16x16x32_bf16 v[106:109], v[142:145], v[196:199], v[106:109]
	v_mfma_f32_16x16x32_bf16 v[94:97], v[134:137], v[204:207], v[94:97]
	v_mfma_f32_16x16x32_bf16 v[90:93], v[142:145], v[204:207], v[90:93]
	v_mfma_f32_16x16x32_bf16 v[78:81], v[134:137], v[212:215], v[78:81]
	v_mfma_f32_16x16x32_bf16 v[74:77], v[142:145], v[212:215], v[74:77]
	v_mfma_f32_16x16x32_bf16 v[118:121], v[164:167], v[184:187], v[118:121]
	v_mfma_f32_16x16x32_bf16 v[114:117], v[172:175], v[184:187], v[114:117]
	v_mfma_f32_16x16x32_bf16 v[102:105], v[164:167], v[192:195], v[102:105]
	v_mfma_f32_16x16x32_bf16 v[98:101], v[172:175], v[192:195], v[98:101]
	v_mfma_f32_16x16x32_bf16 v[86:89], v[164:167], v[200:203], v[86:89]
	v_mfma_f32_16x16x32_bf16 v[82:85], v[172:175], v[200:203], v[82:85]
	v_mfma_f32_16x16x32_bf16 v[70:73], v[164:167], v[208:211], v[70:73]
	v_mfma_f32_16x16x32_bf16 v[66:69], v[172:175], v[208:211], v[66:69]
	v_mfma_f32_16x16x32_bf16 v[118:121], v[168:171], v[188:191], v[118:121]
	v_mfma_f32_16x16x32_bf16 v[114:117], v[180:183], v[188:191], v[114:117]
	v_mfma_f32_16x16x32_bf16 v[102:105], v[168:171], v[196:199], v[102:105]
	v_mfma_f32_16x16x32_bf16 v[98:101], v[180:183], v[196:199], v[98:101]
	v_mfma_f32_16x16x32_bf16 v[86:89], v[168:171], v[204:207], v[86:89]
	v_mfma_f32_16x16x32_bf16 v[82:85], v[180:183], v[204:207], v[82:85]
	v_mfma_f32_16x16x32_bf16 v[70:73], v[168:171], v[212:215], v[70:73]
	v_mfma_f32_16x16x32_bf16 v[66:69], v[180:183], v[212:215], v[66:69]
	s_setprio 0
	s_barrier
	s_add_i32 s9, s9, s41
	v_lshl_add_u64 v[148:149], v[148:149], 0, s[70:71]
	s_mov_b32 m0, s9
	ds_read_b128 v[184:187], v179 offset:49152
	ds_read_b128 v[188:191], v179 offset:50176
	ds_read_b128 v[192:195], v179 offset:51200
	ds_read_b128 v[196:199], v179 offset:52224
	ds_read_b128 v[200:203], v179 offset:53248
	ds_read_b128 v[204:207], v179 offset:54272
	ds_read_b128 v[208:211], v179 offset:55296
	ds_read_b128 v[212:215], v179 offset:56320
	global_load_lds_dwordx4 v[148:149], off
	s_add_i32 m0, s9, 0x2000
	s_add_u32 s26, s26, 0x40080
	v_lshl_add_u64 v[148:149], v[150:151], 0, s[70:71]
	s_addc_u32 s27, s27, 0
	s_add_i32 s9, s78, s41
	global_load_lds_dwordx4 v[148:149], off
	v_lshl_add_u64 v[148:149], s[26:27], 0, v[0:1]
	s_mov_b32 m0, s9
	s_nop 0
	global_load_lds_dwordx4 v[148:149], off
	v_lshl_add_u64 v[148:149], s[26:27], 0, v[158:159]
	s_add_i32 m0, s9, 0x2000
	s_nop 0
	global_load_lds_dwordx4 v[148:149], off
	v_lshl_add_u64 v[148:149], v[216:217], 0, s[70:71]
	s_mov_b32 m0, s50
	s_nop 0
	global_load_lds_dwordx4 v[148:149], off
	v_lshl_add_u64 v[148:149], v[218:219], 0, s[70:71]
	s_mov_b32 m0, s51
	s_nop 0
	global_load_lds_dwordx4 v[148:149], off
	s_waitcnt vmcnt(8)
	s_waitcnt lgkmcnt(0)
	s_barrier
	s_setprio 1
	v_mfma_f32_16x16x32_bf16 v[62:65], v[130:133], v[184:187], v[62:65]
	v_mfma_f32_16x16x32_bf16 v[58:61], v[138:141], v[184:187], v[58:61]
	v_mfma_f32_16x16x32_bf16 v[46:49], v[130:133], v[192:195], v[46:49]
	v_mfma_f32_16x16x32_bf16 v[42:45], v[138:141], v[192:195], v[42:45]
	v_mfma_f32_16x16x32_bf16 v[30:33], v[130:133], v[200:203], v[30:33]
	v_mfma_f32_16x16x32_bf16 v[26:29], v[138:141], v[200:203], v[26:29]
	v_mfma_f32_16x16x32_bf16 v[14:17], v[130:133], v[208:211], v[14:17]
	v_mfma_f32_16x16x32_bf16 v[10:13], v[138:141], v[208:211], v[10:13]
	v_mfma_f32_16x16x32_bf16 v[62:65], v[134:137], v[188:191], v[62:65]
	v_mfma_f32_16x16x32_bf16 v[58:61], v[142:145], v[188:191], v[58:61]
	v_mfma_f32_16x16x32_bf16 v[46:49], v[134:137], v[196:199], v[46:49]
	v_mfma_f32_16x16x32_bf16 v[42:45], v[142:145], v[196:199], v[42:45]
	v_mfma_f32_16x16x32_bf16 v[30:33], v[134:137], v[204:207], v[30:33]
	v_mfma_f32_16x16x32_bf16 v[26:29], v[142:145], v[204:207], v[26:29]
	v_mfma_f32_16x16x32_bf16 v[14:17], v[134:137], v[212:215], v[14:17]
	v_mfma_f32_16x16x32_bf16 v[10:13], v[142:145], v[212:215], v[10:13]
	v_mfma_f32_16x16x32_bf16 v[54:57], v[164:167], v[184:187], v[54:57]
	v_mfma_f32_16x16x32_bf16 v[50:53], v[172:175], v[184:187], v[50:53]
	v_mfma_f32_16x16x32_bf16 v[38:41], v[164:167], v[192:195], v[38:41]
	v_mfma_f32_16x16x32_bf16 v[34:37], v[172:175], v[192:195], v[34:37]
	v_mfma_f32_16x16x32_bf16 v[22:25], v[164:167], v[200:203], v[22:25]
	v_mfma_f32_16x16x32_bf16 v[18:21], v[172:175], v[200:203], v[18:21]
	v_mfma_f32_16x16x32_bf16 v[6:9], v[164:167], v[208:211], v[6:9]
	v_mfma_f32_16x16x32_bf16 v[2:5], v[172:175], v[208:211], v[2:5]
	v_mfma_f32_16x16x32_bf16 v[54:57], v[168:171], v[188:191], v[54:57]
	v_mfma_f32_16x16x32_bf16 v[50:53], v[180:183], v[188:191], v[50:53]
	v_mfma_f32_16x16x32_bf16 v[38:41], v[168:171], v[196:199], v[38:41]
	v_mfma_f32_16x16x32_bf16 v[34:37], v[180:183], v[196:199], v[34:37]
	v_mfma_f32_16x16x32_bf16 v[22:25], v[168:171], v[204:207], v[22:25]
	v_mfma_f32_16x16x32_bf16 v[18:21], v[180:183], v[204:207], v[18:21]
	v_mfma_f32_16x16x32_bf16 v[6:9], v[168:171], v[212:215], v[6:9]
	v_mfma_f32_16x16x32_bf16 v[2:5], v[180:183], v[212:215], v[2:5]
	s_setprio 0
	s_barrier
	s_add_u32 s60, s60, 0x100
	s_addc_u32 s61, s61, 0
	s_add_u32 s28, s28, 0x100
	s_addc_u32 s29, s29, 0
	s_cmp_ge_u32 s75, s17
	s_mov_b32 s26, s75
	s_cbranch_scc0 .LBB0_701
	s_and_b64 vcc, exec, s[14:15]
	s_cbranch_vccz .LBB0_704

.LBB0_846:
	s_add_u32 s9, s96, 0xfffc0080
	s_addc_u32 s38, s97, -1
	s_add_i32 s78, 0, 0x10000
	s_cmp_eq_u32 s75, 12
	s_cselect_b32 vcc_hi, s25, s38
	s_cselect_b32 vcc_lo, s28, s9
	v_add_u32_e32 v148, s78, v145
	s_cselect_b32 s39, s23, s61
	s_cselect_b32 s38, s29, s53
	s_add_i32 s9, 0, 0x14000
	ds_read_b128 v[140:143], v148
	ds_read_b128 v[156:159], v148 offset:1024
	ds_read_b128 v[160:163], v148 offset:2048
	ds_read_b128 v[164:167], v148 offset:3072
	v_add_u32_e32 v148, s9, v145
	ds_read_b128 v[168:171], v148
	ds_read_b128 v[172:175], v148 offset:1024
	ds_read_b128 v[176:179], v148 offset:2048
	ds_read_b128 v[180:183], v148 offset:3072
	v_lshl_add_u64 v[148:149], s[96:97], 0, v[136:137]
	s_add_i32 m0, s46, 0xc000
	ds_read_b128 v[184:187], v147
	ds_read_b128 v[188:191], v147 offset:1024
	ds_read_b128 v[192:195], v147 offset:2048
	ds_read_b128 v[196:199], v147 offset:3072
	ds_read_b128 v[200:203], v147 offset:4096
	ds_read_b128 v[204:207], v147 offset:5120
	ds_read_b128 v[208:211], v147 offset:6144
	ds_read_b128 v[212:215], v147 offset:7168
	global_load_lds_dwordx4 v[148:149], off
	v_lshl_add_u64 v[148:149], s[96:97], 0, v[138:139]
	s_add_i32 m0, s46, 0xe000
	s_nop 0
	global_load_lds_dwordx4 v[148:149], off
	s_waitcnt vmcnt(8)
	s_waitcnt lgkmcnt(0)
	s_barrier
	s_setprio 1
	v_mfma_f32_16x16x32_bf16 v[126:129], v[140:143], v[184:187], v[126:129]
	v_mfma_f32_16x16x32_bf16 v[118:121], v[160:163], v[184:187], v[118:121]
	v_mfma_f32_16x16x32_bf16 v[110:113], v[140:143], v[192:195], v[110:113]
	v_mfma_f32_16x16x32_bf16 v[102:105], v[160:163], v[192:195], v[102:105]
	v_mfma_f32_16x16x32_bf16 v[94:97], v[140:143], v[200:203], v[94:97]
	v_mfma_f32_16x16x32_bf16 v[86:89], v[160:163], v[200:203], v[86:89]
	v_mfma_f32_16x16x32_bf16 v[78:81], v[140:143], v[208:211], v[78:81]
	v_mfma_f32_16x16x32_bf16 v[70:73], v[160:163], v[208:211], v[70:73]
	v_mfma_f32_16x16x32_bf16 v[126:129], v[156:159], v[188:191], v[126:129]
	v_mfma_f32_16x16x32_bf16 v[118:121], v[164:167], v[188:191], v[118:121]
	v_mfma_f32_16x16x32_bf16 v[110:113], v[156:159], v[196:199], v[110:113]
	v_mfma_f32_16x16x32_bf16 v[102:105], v[164:167], v[196:199], v[102:105]
	v_mfma_f32_16x16x32_bf16 v[94:97], v[156:159], v[204:207], v[94:97]
	v_mfma_f32_16x16x32_bf16 v[86:89], v[164:167], v[204:207], v[86:89]
	v_mfma_f32_16x16x32_bf16 v[78:81], v[156:159], v[212:215], v[78:81]
	v_mfma_f32_16x16x32_bf16 v[70:73], v[164:167], v[212:215], v[70:73]
	v_mfma_f32_16x16x32_bf16 v[122:125], v[168:171], v[184:187], v[122:125]
	v_mfma_f32_16x16x32_bf16 v[114:117], v[176:179], v[184:187], v[114:117]
	v_mfma_f32_16x16x32_bf16 v[106:109], v[168:171], v[192:195], v[106:109]
	v_mfma_f32_16x16x32_bf16 v[98:101], v[176:179], v[192:195], v[98:101]
	v_mfma_f32_16x16x32_bf16 v[90:93], v[168:171], v[200:203], v[90:93]
	v_mfma_f32_16x16x32_bf16 v[82:85], v[176:179], v[200:203], v[82:85]
	v_mfma_f32_16x16x32_bf16 v[74:77], v[168:171], v[208:211], v[74:77]
	v_mfma_f32_16x16x32_bf16 v[66:69], v[176:179], v[208:211], v[66:69]
	v_mfma_f32_16x16x32_bf16 v[122:125], v[172:175], v[188:191], v[122:125]
	v_mfma_f32_16x16x32_bf16 v[114:117], v[180:183], v[188:191], v[114:117]
	v_mfma_f32_16x16x32_bf16 v[106:109], v[172:175], v[196:199], v[106:109]
	v_mfma_f32_16x16x32_bf16 v[98:101], v[180:183], v[196:199], v[98:101]
	v_mfma_f32_16x16x32_bf16 v[90:93], v[172:175], v[204:207], v[90:93]
	v_mfma_f32_16x16x32_bf16 v[82:85], v[180:183], v[204:207], v[82:85]
	v_mfma_f32_16x16x32_bf16 v[74:77], v[172:175], v[212:215], v[74:77]
	v_mfma_f32_16x16x32_bf16 v[66:69], v[180:183], v[212:215], v[66:69]
	s_setprio 0
	s_barrier
	s_add_i32 s78, s78, s45
	v_lshl_add_u64 v[148:149], s[38:39], 0, v[0:1]
	s_mov_b32 m0, s78
	ds_read_b128 v[184:187], v147 offset:16384
	ds_read_b128 v[188:191], v147 offset:17408
	ds_read_b128 v[192:195], v147 offset:18432
	ds_read_b128 v[196:199], v147 offset:19456
	ds_read_b128 v[200:203], v147 offset:20480
	ds_read_b128 v[204:207], v147 offset:21504
	ds_read_b128 v[208:211], v147 offset:22528
	ds_read_b128 v[212:215], v147 offset:23552
	global_load_lds_dwordx4 v[148:149], off
	s_add_i32 m0, s78, 0x2000
	s_add_u32 s78, s38, 0x40000
	v_lshl_add_u64 v[150:151], s[38:39], 0, v[134:135]
	s_addc_u32 s79, s39, 0
	s_add_i32 s9, s9, s45
	global_load_lds_dwordx4 v[150:151], off
	v_lshl_add_u64 v[216:217], s[78:79], 0, v[0:1]
	s_mov_b32 m0, s9
	v_lshl_add_u64 v[218:219], vcc, 0, v[132:133]
	global_load_lds_dwordx4 v[216:217], off
	v_lshl_add_u64 v[216:217], s[78:79], 0, v[134:135]
	s_add_i32 m0, s9, 0x2000
	s_nop 0
	global_load_lds_dwordx4 v[216:217], off
	v_lshl_add_u64 v[216:217], vcc, 0, v[130:131]
	s_mov_b32 m0, s46
	s_nop 0
	global_load_lds_dwordx4 v[216:217], off
	s_mov_b32 m0, s47
	s_nop 0
	global_load_lds_dwordx4 v[218:219], off
	s_waitcnt vmcnt(8)
	s_waitcnt lgkmcnt(0)
	s_barrier
	s_setprio 1
	v_mfma_f32_16x16x32_bf16 v[62:65], v[140:143], v[184:187], v[62:65]
	v_mfma_f32_16x16x32_bf16 v[54:57], v[160:163], v[184:187], v[54:57]
	v_mfma_f32_16x16x32_bf16 v[46:49], v[140:143], v[192:195], v[46:49]
	v_mfma_f32_16x16x32_bf16 v[38:41], v[160:163], v[192:195], v[38:41]
	v_mfma_f32_16x16x32_bf16 v[30:33], v[140:143], v[200:203], v[30:33]
	v_mfma_f32_16x16x32_bf16 v[22:25], v[160:163], v[200:203], v[22:25]
	v_mfma_f32_16x16x32_bf16 v[14:17], v[140:143], v[208:211], v[14:17]
	v_mfma_f32_16x16x32_bf16 v[6:9], v[160:163], v[208:211], v[6:9]
	v_mfma_f32_16x16x32_bf16 v[62:65], v[156:159], v[188:191], v[62:65]
	v_mfma_f32_16x16x32_bf16 v[54:57], v[164:167], v[188:191], v[54:57]
	v_mfma_f32_16x16x32_bf16 v[46:49], v[156:159], v[196:199], v[46:49]
	v_mfma_f32_16x16x32_bf16 v[38:41], v[164:167], v[196:199], v[38:41]
	v_mfma_f32_16x16x32_bf16 v[30:33], v[156:159], v[204:207], v[30:33]
	v_mfma_f32_16x16x32_bf16 v[22:25], v[164:167], v[204:207], v[22:25]
	v_mfma_f32_16x16x32_bf16 v[14:17], v[156:159], v[212:215], v[14:17]
	v_mfma_f32_16x16x32_bf16 v[6:9], v[164:167], v[212:215], v[6:9]
	v_mfma_f32_16x16x32_bf16 v[58:61], v[168:171], v[184:187], v[58:61]
	v_mfma_f32_16x16x32_bf16 v[50:53], v[176:179], v[184:187], v[50:53]
	v_mfma_f32_16x16x32_bf16 v[42:45], v[168:171], v[192:195], v[42:45]
	v_mfma_f32_16x16x32_bf16 v[34:37], v[176:179], v[192:195], v[34:37]
	v_mfma_f32_16x16x32_bf16 v[26:29], v[168:171], v[200:203], v[26:29]
	v_mfma_f32_16x16x32_bf16 v[18:21], v[176:179], v[200:203], v[18:21]
	v_mfma_f32_16x16x32_bf16 v[10:13], v[168:171], v[208:211], v[10:13]
	v_mfma_f32_16x16x32_bf16 v[2:5], v[176:179], v[208:211], v[2:5]
	v_mfma_f32_16x16x32_bf16 v[58:61], v[172:175], v[188:191], v[58:61]
	v_mfma_f32_16x16x32_bf16 v[50:53], v[180:183], v[188:191], v[50:53]
	v_mfma_f32_16x16x32_bf16 v[42:45], v[172:175], v[196:199], v[42:45]
	v_mfma_f32_16x16x32_bf16 v[34:37], v[180:183], v[196:199], v[34:37]
	v_mfma_f32_16x16x32_bf16 v[26:29], v[172:175], v[204:207], v[26:29]
	v_mfma_f32_16x16x32_bf16 v[18:21], v[180:183], v[204:207], v[18:21]
	v_mfma_f32_16x16x32_bf16 v[10:13], v[172:175], v[212:215], v[10:13]
	v_mfma_f32_16x16x32_bf16 v[2:5], v[180:183], v[212:215], v[2:5]
	s_setprio 0
	s_barrier
	s_add_i32 s9, 0, 0x18000
	s_add_i32 s83, 0, 0x1c000
	v_add_u32_e32 v164, s9, v145
	v_add_u32_e32 v180, s83, v145
	ds_read_b128 v[140:143], v164
	ds_read_b128 v[156:159], v164 offset:1024
	ds_read_b128 v[160:163], v164 offset:2048
	ds_read_b128 v[164:167], v164 offset:3072
	ds_read_b128 v[168:171], v180
	ds_read_b128 v[172:175], v180 offset:1024
	ds_read_b128 v[176:179], v180 offset:2048
	ds_read_b128 v[180:183], v180 offset:3072
	s_add_u32 s78, vcc_lo, 0x40000
	s_addc_u32 s79, vcc_hi, 0
	s_mov_b32 m0, s48
	v_lshl_add_u64 v[220:221], s[78:79], 0, v[130:131]
	ds_read_b128 v[184:187], v147 offset:32768
	ds_read_b128 v[188:191], v147 offset:33792
	ds_read_b128 v[192:195], v147 offset:34816
	ds_read_b128 v[196:199], v147 offset:35840
	ds_read_b128 v[200:203], v147 offset:36864
	ds_read_b128 v[204:207], v147 offset:37888
	ds_read_b128 v[208:211], v147 offset:38912
	ds_read_b128 v[212:215], v147 offset:39936
	global_load_lds_dwordx4 v[220:221], off
	v_lshl_add_u64 v[220:221], s[78:79], 0, v[132:133]
	s_mov_b32 m0, s49
	s_nop 0
	global_load_lds_dwordx4 v[220:221], off
	s_waitcnt vmcnt(8)
	s_waitcnt lgkmcnt(0)
	s_barrier
	s_setprio 1
	v_mfma_f32_16x16x32_bf16 v[126:129], v[140:143], v[184:187], v[126:129]
	v_mfma_f32_16x16x32_bf16 v[118:121], v[160:163], v[184:187], v[118:121]
	v_mfma_f32_16x16x32_bf16 v[110:113], v[140:143], v[192:195], v[110:113]
	v_mfma_f32_16x16x32_bf16 v[102:105], v[160:163], v[192:195], v[102:105]
	v_mfma_f32_16x16x32_bf16 v[94:97], v[140:143], v[200:203], v[94:97]
	v_mfma_f32_16x16x32_bf16 v[86:89], v[160:163], v[200:203], v[86:89]
	v_mfma_f32_16x16x32_bf16 v[78:81], v[140:143], v[208:211], v[78:81]
	v_mfma_f32_16x16x32_bf16 v[70:73], v[160:163], v[208:211], v[70:73]
	v_mfma_f32_16x16x32_bf16 v[126:129], v[156:159], v[188:191], v[126:129]
	v_mfma_f32_16x16x32_bf16 v[118:121], v[164:167], v[188:191], v[118:121]
	v_mfma_f32_16x16x32_bf16 v[110:113], v[156:159], v[196:199], v[110:113]
	v_mfma_f32_16x16x32_bf16 v[102:105], v[164:167], v[196:199], v[102:105]
	v_mfma_f32_16x16x32_bf16 v[94:97], v[156:159], v[204:207], v[94:97]
	v_mfma_f32_16x16x32_bf16 v[86:89], v[164:167], v[204:207], v[86:89]
	v_mfma_f32_16x16x32_bf16 v[78:81], v[156:159], v[212:215], v[78:81]
	v_mfma_f32_16x16x32_bf16 v[70:73], v[164:167], v[212:215], v[70:73]
	v_mfma_f32_16x16x32_bf16 v[122:125], v[168:171], v[184:187], v[122:125]
	v_mfma_f32_16x16x32_bf16 v[114:117], v[176:179], v[184:187], v[114:117]
	v_mfma_f32_16x16x32_bf16 v[106:109], v[168:171], v[192:195], v[106:109]
	v_mfma_f32_16x16x32_bf16 v[98:101], v[176:179], v[192:195], v[98:101]
	v_mfma_f32_16x16x32_bf16 v[90:93], v[168:171], v[200:203], v[90:93]
	v_mfma_f32_16x16x32_bf16 v[82:85], v[176:179], v[200:203], v[82:85]
	v_mfma_f32_16x16x32_bf16 v[74:77], v[168:171], v[208:211], v[74:77]
	v_mfma_f32_16x16x32_bf16 v[66:69], v[176:179], v[208:211], v[66:69]
	v_mfma_f32_16x16x32_bf16 v[122:125], v[172:175], v[188:191], v[122:125]
	v_mfma_f32_16x16x32_bf16 v[114:117], v[180:183], v[188:191], v[114:117]
	v_mfma_f32_16x16x32_bf16 v[106:109], v[172:175], v[196:199], v[106:109]
	v_mfma_f32_16x16x32_bf16 v[98:101], v[180:183], v[196:199], v[98:101]
	v_mfma_f32_16x16x32_bf16 v[90:93], v[172:175], v[204:207], v[90:93]
	v_mfma_f32_16x16x32_bf16 v[82:85], v[180:183], v[204:207], v[82:85]
	v_mfma_f32_16x16x32_bf16 v[74:77], v[172:175], v[212:215], v[74:77]
	v_mfma_f32_16x16x32_bf16 v[66:69], v[180:183], v[212:215], v[66:69]
	s_setprio 0
	s_barrier
	s_add_i32 s9, s9, s45
	v_lshl_add_u64 v[148:149], v[148:149], 0, s[70:71]
	s_mov_b32 m0, s9
	ds_read_b128 v[184:187], v147 offset:49152
	ds_read_b128 v[188:191], v147 offset:50176
	ds_read_b128 v[192:195], v147 offset:51200
	ds_read_b128 v[196:199], v147 offset:52224
	ds_read_b128 v[200:203], v147 offset:53248
	ds_read_b128 v[204:207], v147 offset:54272
	ds_read_b128 v[208:211], v147 offset:55296
	ds_read_b128 v[212:215], v147 offset:56320
	global_load_lds_dwordx4 v[148:149], off
	s_add_i32 m0, s9, 0x2000
	s_add_u32 s38, s38, 0x40080
	v_lshl_add_u64 v[148:149], v[150:151], 0, s[70:71]
	s_addc_u32 s39, s39, 0
	s_add_i32 s9, s83, s45
	global_load_lds_dwordx4 v[148:149], off
	v_lshl_add_u64 v[148:149], s[38:39], 0, v[0:1]
	s_mov_b32 m0, s9
	s_nop 0
	global_load_lds_dwordx4 v[148:149], off
	v_lshl_add_u64 v[148:149], s[38:39], 0, v[134:135]
	s_add_i32 m0, s9, 0x2000
	s_nop 0
	global_load_lds_dwordx4 v[148:149], off
	v_lshl_add_u64 v[148:149], v[216:217], 0, s[70:71]
	s_mov_b32 m0, s50
	s_nop 0
	global_load_lds_dwordx4 v[148:149], off
	v_lshl_add_u64 v[148:149], v[218:219], 0, s[70:71]
	s_mov_b32 m0, s51
	s_nop 0
	global_load_lds_dwordx4 v[148:149], off
	s_waitcnt vmcnt(8)
	s_waitcnt lgkmcnt(0)
	s_barrier
	s_setprio 1
	v_mfma_f32_16x16x32_bf16 v[62:65], v[140:143], v[184:187], v[62:65]
	v_mfma_f32_16x16x32_bf16 v[54:57], v[160:163], v[184:187], v[54:57]
	v_mfma_f32_16x16x32_bf16 v[46:49], v[140:143], v[192:195], v[46:49]
	v_mfma_f32_16x16x32_bf16 v[38:41], v[160:163], v[192:195], v[38:41]
	v_mfma_f32_16x16x32_bf16 v[30:33], v[140:143], v[200:203], v[30:33]
	v_mfma_f32_16x16x32_bf16 v[22:25], v[160:163], v[200:203], v[22:25]
	v_mfma_f32_16x16x32_bf16 v[14:17], v[140:143], v[208:211], v[14:17]
	v_mfma_f32_16x16x32_bf16 v[6:9], v[160:163], v[208:211], v[6:9]
	v_mfma_f32_16x16x32_bf16 v[62:65], v[156:159], v[188:191], v[62:65]
	v_mfma_f32_16x16x32_bf16 v[54:57], v[164:167], v[188:191], v[54:57]
	v_mfma_f32_16x16x32_bf16 v[46:49], v[156:159], v[196:199], v[46:49]
	v_mfma_f32_16x16x32_bf16 v[38:41], v[164:167], v[196:199], v[38:41]
	v_mfma_f32_16x16x32_bf16 v[30:33], v[156:159], v[204:207], v[30:33]
	v_mfma_f32_16x16x32_bf16 v[22:25], v[164:167], v[204:207], v[22:25]
	v_mfma_f32_16x16x32_bf16 v[14:17], v[156:159], v[212:215], v[14:17]
	v_mfma_f32_16x16x32_bf16 v[6:9], v[164:167], v[212:215], v[6:9]
	v_mfma_f32_16x16x32_bf16 v[58:61], v[168:171], v[184:187], v[58:61]
	v_mfma_f32_16x16x32_bf16 v[50:53], v[176:179], v[184:187], v[50:53]
	v_mfma_f32_16x16x32_bf16 v[42:45], v[168:171], v[192:195], v[42:45]
	v_mfma_f32_16x16x32_bf16 v[34:37], v[176:179], v[192:195], v[34:37]
	v_mfma_f32_16x16x32_bf16 v[26:29], v[168:171], v[200:203], v[26:29]
	v_mfma_f32_16x16x32_bf16 v[18:21], v[176:179], v[200:203], v[18:21]
	v_mfma_f32_16x16x32_bf16 v[10:13], v[168:171], v[208:211], v[10:13]
	v_mfma_f32_16x16x32_bf16 v[2:5], v[176:179], v[208:211], v[2:5]
	v_mfma_f32_16x16x32_bf16 v[58:61], v[172:175], v[188:191], v[58:61]
	v_mfma_f32_16x16x32_bf16 v[50:53], v[180:183], v[188:191], v[50:53]
	v_mfma_f32_16x16x32_bf16 v[42:45], v[172:175], v[196:199], v[42:45]
	v_mfma_f32_16x16x32_bf16 v[34:37], v[180:183], v[196:199], v[34:37]
	v_mfma_f32_16x16x32_bf16 v[26:29], v[172:175], v[204:207], v[26:29]
	v_mfma_f32_16x16x32_bf16 v[18:21], v[180:183], v[204:207], v[18:21]
	v_mfma_f32_16x16x32_bf16 v[10:13], v[172:175], v[212:215], v[10:13]
	v_mfma_f32_16x16x32_bf16 v[2:5], v[180:183], v[212:215], v[2:5]
	s_setprio 0
	s_barrier
	s_add_i32 s75, s75, 2
	s_add_u32 s96, s96, 0x100
	s_addc_u32 s97, s97, 0
	s_add_u32 s53, s53, 0x100
	s_addc_u32 s61, s61, 0
	s_cmp_gt_u32 s75, 13
	s_cbranch_scc0 .LBB0_846
	s_and_b64 vcc, exec, s[14:15]
	s_cbranch_vccz .LBB0_849
	s_barrier

.LBB0_950:
	s_add_i32 s9, s26, 2
	s_add_u32 s60, s38, 0x100
	s_addc_u32 s61, s39, 0
	s_add_i32 s78, 0, 0x10000
	s_cmp_eq_u32 s29, s26
	s_cselect_b32 s73, s25, s61
	s_cselect_b32 s72, s24, s60
	s_cselect_b32 s27, s37, vcc_hi
	s_cselect_b32 s26, s36, vcc_lo
	s_add_i32 s79, 0, 0x14000
	v_add_u32_e32 v156, s78, v177
	v_add_u32_e32 v172, s79, v177
	ds_read_b128 v[140:143], v156
	ds_read_b128 v[144:147], v156 offset:1024
	ds_read_b128 v[148:151], v156 offset:2048
	ds_read_b128 v[156:159], v156 offset:3072
	ds_read_b128 v[160:163], v172
	ds_read_b128 v[164:167], v172 offset:1024
	ds_read_b128 v[168:171], v172 offset:2048
	ds_read_b128 v[172:175], v172 offset:3072
	v_lshl_add_u64 v[212:213], s[38:39], 0, v[136:137]
	s_add_i32 m0, s50, 0xc000
	ds_read_b128 v[180:183], v179
	ds_read_b128 v[184:187], v179 offset:1024
	ds_read_b128 v[188:191], v179 offset:2048
	ds_read_b128 v[192:195], v179 offset:3072
	ds_read_b128 v[196:199], v179 offset:4096
	ds_read_b128 v[200:203], v179 offset:5120
	ds_read_b128 v[204:207], v179 offset:6144
	ds_read_b128 v[208:211], v179 offset:7168
	global_load_lds_dwordx4 v[212:213], off
	v_lshl_add_u64 v[212:213], s[38:39], 0, v[138:139]
	s_add_i32 m0, s50, 0xe000
	s_nop 0
	global_load_lds_dwordx4 v[212:213], off
	s_waitcnt vmcnt(8)
	s_waitcnt lgkmcnt(0)
	s_barrier
	s_setprio 1
	v_mfma_f32_16x16x32_bf16 v[126:129], v[140:143], v[180:183], v[126:129]
	v_mfma_f32_16x16x32_bf16 v[122:125], v[148:151], v[180:183], v[122:125]
	v_mfma_f32_16x16x32_bf16 v[110:113], v[140:143], v[188:191], v[110:113]
	v_mfma_f32_16x16x32_bf16 v[106:109], v[148:151], v[188:191], v[106:109]
	v_mfma_f32_16x16x32_bf16 v[94:97], v[140:143], v[196:199], v[94:97]
	v_mfma_f32_16x16x32_bf16 v[90:93], v[148:151], v[196:199], v[90:93]
	v_mfma_f32_16x16x32_bf16 v[78:81], v[140:143], v[204:207], v[78:81]
	v_mfma_f32_16x16x32_bf16 v[74:77], v[148:151], v[204:207], v[74:77]
	v_mfma_f32_16x16x32_bf16 v[126:129], v[144:147], v[184:187], v[126:129]
	v_mfma_f32_16x16x32_bf16 v[122:125], v[156:159], v[184:187], v[122:125]
	v_mfma_f32_16x16x32_bf16 v[110:113], v[144:147], v[192:195], v[110:113]
	v_mfma_f32_16x16x32_bf16 v[106:109], v[156:159], v[192:195], v[106:109]
	v_mfma_f32_16x16x32_bf16 v[94:97], v[144:147], v[200:203], v[94:97]
	v_mfma_f32_16x16x32_bf16 v[90:93], v[156:159], v[200:203], v[90:93]
	v_mfma_f32_16x16x32_bf16 v[78:81], v[144:147], v[208:211], v[78:81]
	v_mfma_f32_16x16x32_bf16 v[74:77], v[156:159], v[208:211], v[74:77]
	v_mfma_f32_16x16x32_bf16 v[118:121], v[160:163], v[180:183], v[118:121]
	v_mfma_f32_16x16x32_bf16 v[114:117], v[168:171], v[180:183], v[114:117]
	v_mfma_f32_16x16x32_bf16 v[102:105], v[160:163], v[188:191], v[102:105]
	v_mfma_f32_16x16x32_bf16 v[98:101], v[168:171], v[188:191], v[98:101]
	v_mfma_f32_16x16x32_bf16 v[86:89], v[160:163], v[196:199], v[86:89]
	v_mfma_f32_16x16x32_bf16 v[82:85], v[168:171], v[196:199], v[82:85]
	v_mfma_f32_16x16x32_bf16 v[70:73], v[160:163], v[204:207], v[70:73]
	v_mfma_f32_16x16x32_bf16 v[66:69], v[168:171], v[204:207], v[66:69]
	v_mfma_f32_16x16x32_bf16 v[118:121], v[164:167], v[184:187], v[118:121]
	v_mfma_f32_16x16x32_bf16 v[114:117], v[172:175], v[184:187], v[114:117]
	v_mfma_f32_16x16x32_bf16 v[102:105], v[164:167], v[192:195], v[102:105]
	v_mfma_f32_16x16x32_bf16 v[98:101], v[172:175], v[192:195], v[98:101]
	v_mfma_f32_16x16x32_bf16 v[86:89], v[164:167], v[200:203], v[86:89]
	v_mfma_f32_16x16x32_bf16 v[82:85], v[172:175], v[200:203], v[82:85]
	v_mfma_f32_16x16x32_bf16 v[70:73], v[164:167], v[208:211], v[70:73]
	v_mfma_f32_16x16x32_bf16 v[66:69], v[172:175], v[208:211], v[66:69]
	s_setprio 0
	s_barrier
	s_add_i32 s38, s78, s49
	v_lshl_add_u64 v[212:213], s[26:27], 0, v[0:1]
	s_mov_b32 m0, s38
	ds_read_b128 v[180:183], v179 offset:16384
	ds_read_b128 v[184:187], v179 offset:17408
	ds_read_b128 v[188:191], v179 offset:18432
	ds_read_b128 v[192:195], v179 offset:19456
	ds_read_b128 v[196:199], v179 offset:20480
	ds_read_b128 v[200:203], v179 offset:21504
	ds_read_b128 v[204:207], v179 offset:22528
	ds_read_b128 v[208:211], v179 offset:23552
	global_load_lds_dwordx4 v[212:213], off
	s_add_i32 m0, s38, 0x2000
	s_add_u32 s38, s26, 0xb0000
	v_lshl_add_u64 v[214:215], s[26:27], 0, v[134:135]
	s_addc_u32 s39, s27, 0
	s_add_i32 s78, s79, s49
	global_load_lds_dwordx4 v[214:215], off
	v_lshl_add_u64 v[216:217], s[38:39], 0, v[0:1]
	s_mov_b32 m0, s78
	v_lshl_add_u64 v[218:219], s[72:73], 0, v[132:133]
	global_load_lds_dwordx4 v[216:217], off
	v_lshl_add_u64 v[216:217], s[38:39], 0, v[134:135]
	s_add_i32 m0, s78, 0x2000
	s_nop 0
	global_load_lds_dwordx4 v[216:217], off
	v_lshl_add_u64 v[216:217], s[72:73], 0, v[130:131]
	s_mov_b32 m0, s50
	s_nop 0
	global_load_lds_dwordx4 v[216:217], off
	s_mov_b32 m0, s51
	s_nop 0
	global_load_lds_dwordx4 v[218:219], off
	s_waitcnt vmcnt(8)
	s_waitcnt lgkmcnt(0)
	s_barrier
	s_setprio 1
	v_mfma_f32_16x16x32_bf16 v[62:65], v[140:143], v[180:183], v[62:65]
	v_mfma_f32_16x16x32_bf16 v[58:61], v[148:151], v[180:183], v[58:61]
	v_mfma_f32_16x16x32_bf16 v[46:49], v[140:143], v[188:191], v[46:49]
	v_mfma_f32_16x16x32_bf16 v[42:45], v[148:151], v[188:191], v[42:45]
	v_mfma_f32_16x16x32_bf16 v[30:33], v[140:143], v[196:199], v[30:33]
	v_mfma_f32_16x16x32_bf16 v[26:29], v[148:151], v[196:199], v[26:29]
	v_mfma_f32_16x16x32_bf16 v[14:17], v[140:143], v[204:207], v[14:17]
	v_mfma_f32_16x16x32_bf16 v[10:13], v[148:151], v[204:207], v[10:13]
	v_mfma_f32_16x16x32_bf16 v[62:65], v[144:147], v[184:187], v[62:65]
	v_mfma_f32_16x16x32_bf16 v[58:61], v[156:159], v[184:187], v[58:61]
	v_mfma_f32_16x16x32_bf16 v[46:49], v[144:147], v[192:195], v[46:49]
	v_mfma_f32_16x16x32_bf16 v[42:45], v[156:159], v[192:195], v[42:45]
	v_mfma_f32_16x16x32_bf16 v[30:33], v[144:147], v[200:203], v[30:33]
	v_mfma_f32_16x16x32_bf16 v[26:29], v[156:159], v[200:203], v[26:29]
	v_mfma_f32_16x16x32_bf16 v[14:17], v[144:147], v[208:211], v[14:17]
	v_mfma_f32_16x16x32_bf16 v[10:13], v[156:159], v[208:211], v[10:13]
	v_mfma_f32_16x16x32_bf16 v[54:57], v[160:163], v[180:183], v[54:57]
	v_mfma_f32_16x16x32_bf16 v[50:53], v[168:171], v[180:183], v[50:53]
	v_mfma_f32_16x16x32_bf16 v[38:41], v[160:163], v[188:191], v[38:41]
	v_mfma_f32_16x16x32_bf16 v[34:37], v[168:171], v[188:191], v[34:37]
	v_mfma_f32_16x16x32_bf16 v[22:25], v[160:163], v[196:199], v[22:25]
	v_mfma_f32_16x16x32_bf16 v[18:21], v[168:171], v[196:199], v[18:21]
	v_mfma_f32_16x16x32_bf16 v[6:9], v[160:163], v[204:207], v[6:9]
	v_mfma_f32_16x16x32_bf16 v[2:5], v[168:171], v[204:207], v[2:5]
	v_mfma_f32_16x16x32_bf16 v[54:57], v[164:167], v[184:187], v[54:57]
	v_mfma_f32_16x16x32_bf16 v[50:53], v[172:175], v[184:187], v[50:53]
	v_mfma_f32_16x16x32_bf16 v[38:41], v[164:167], v[192:195], v[38:41]
	v_mfma_f32_16x16x32_bf16 v[34:37], v[172:175], v[192:195], v[34:37]
	v_mfma_f32_16x16x32_bf16 v[22:25], v[164:167], v[200:203], v[22:25]
	v_mfma_f32_16x16x32_bf16 v[18:21], v[172:175], v[200:203], v[18:21]
	v_mfma_f32_16x16x32_bf16 v[6:9], v[164:167], v[208:211], v[6:9]
	v_mfma_f32_16x16x32_bf16 v[2:5], v[172:175], v[208:211], v[2:5]
	s_setprio 0
	s_barrier
	s_add_i32 s78, 0, 0x18000
	s_add_i32 s79, 0, 0x1c000
	v_add_u32_e32 v156, s78, v177
	v_add_u32_e32 v172, s79, v177
	ds_read_b128 v[140:143], v156
	ds_read_b128 v[144:147], v156 offset:1024
	ds_read_b128 v[148:151], v156 offset:2048
	ds_read_b128 v[156:159], v156 offset:3072
	ds_read_b128 v[160:163], v172
	ds_read_b128 v[164:167], v172 offset:1024
	ds_read_b128 v[168:171], v172 offset:2048
	ds_read_b128 v[172:175], v172 offset:3072
	s_add_u32 s38, s72, 0xb0000
	s_addc_u32 s39, s73, 0
	s_mov_b32 m0, s52
	v_lshl_add_u64 v[220:221], s[38:39], 0, v[130:131]
	ds_read_b128 v[180:183], v179 offset:32768
	ds_read_b128 v[184:187], v179 offset:33792
	ds_read_b128 v[188:191], v179 offset:34816
	ds_read_b128 v[192:195], v179 offset:35840
	ds_read_b128 v[196:199], v179 offset:36864
	ds_read_b128 v[200:203], v179 offset:37888
	ds_read_b128 v[204:207], v179 offset:38912
	ds_read_b128 v[208:211], v179 offset:39936
	global_load_lds_dwordx4 v[220:221], off
	v_lshl_add_u64 v[220:221], s[38:39], 0, v[132:133]
	s_mov_b32 m0, s53
	s_nop 0
	global_load_lds_dwordx4 v[220:221], off
	s_waitcnt vmcnt(8)
	s_waitcnt lgkmcnt(0)
	s_barrier
	s_setprio 1
	v_mfma_f32_16x16x32_bf16 v[126:129], v[140:143], v[180:183], v[126:129]
	v_mfma_f32_16x16x32_bf16 v[122:125], v[148:151], v[180:183], v[122:125]
	v_mfma_f32_16x16x32_bf16 v[110:113], v[140:143], v[188:191], v[110:113]
	v_mfma_f32_16x16x32_bf16 v[106:109], v[148:151], v[188:191], v[106:109]
	v_mfma_f32_16x16x32_bf16 v[94:97], v[140:143], v[196:199], v[94:97]
	v_mfma_f32_16x16x32_bf16 v[90:93], v[148:151], v[196:199], v[90:93]
	v_mfma_f32_16x16x32_bf16 v[78:81], v[140:143], v[204:207], v[78:81]
	v_mfma_f32_16x16x32_bf16 v[74:77], v[148:151], v[204:207], v[74:77]
	v_mfma_f32_16x16x32_bf16 v[126:129], v[144:147], v[184:187], v[126:129]
	v_mfma_f32_16x16x32_bf16 v[122:125], v[156:159], v[184:187], v[122:125]
	v_mfma_f32_16x16x32_bf16 v[110:113], v[144:147], v[192:195], v[110:113]
	v_mfma_f32_16x16x32_bf16 v[106:109], v[156:159], v[192:195], v[106:109]
	v_mfma_f32_16x16x32_bf16 v[94:97], v[144:147], v[200:203], v[94:97]
	v_mfma_f32_16x16x32_bf16 v[90:93], v[156:159], v[200:203], v[90:93]
	v_mfma_f32_16x16x32_bf16 v[78:81], v[144:147], v[208:211], v[78:81]
	v_mfma_f32_16x16x32_bf16 v[74:77], v[156:159], v[208:211], v[74:77]
	v_mfma_f32_16x16x32_bf16 v[118:121], v[160:163], v[180:183], v[118:121]
	v_mfma_f32_16x16x32_bf16 v[114:117], v[168:171], v[180:183], v[114:117]
	v_mfma_f32_16x16x32_bf16 v[102:105], v[160:163], v[188:191], v[102:105]
	v_mfma_f32_16x16x32_bf16 v[98:101], v[168:171], v[188:191], v[98:101]
	v_mfma_f32_16x16x32_bf16 v[86:89], v[160:163], v[196:199], v[86:89]
	v_mfma_f32_16x16x32_bf16 v[82:85], v[168:171], v[196:199], v[82:85]
	v_mfma_f32_16x16x32_bf16 v[70:73], v[160:163], v[204:207], v[70:73]
	v_mfma_f32_16x16x32_bf16 v[66:69], v[168:171], v[204:207], v[66:69]
	v_mfma_f32_16x16x32_bf16 v[118:121], v[164:167], v[184:187], v[118:121]
	v_mfma_f32_16x16x32_bf16 v[114:117], v[172:175], v[184:187], v[114:117]
	v_mfma_f32_16x16x32_bf16 v[102:105], v[164:167], v[192:195], v[102:105]
	v_mfma_f32_16x16x32_bf16 v[98:101], v[172:175], v[192:195], v[98:101]
	v_mfma_f32_16x16x32_bf16 v[86:89], v[164:167], v[200:203], v[86:89]
	v_mfma_f32_16x16x32_bf16 v[82:85], v[172:175], v[200:203], v[82:85]
	v_mfma_f32_16x16x32_bf16 v[70:73], v[164:167], v[208:211], v[70:73]
	v_mfma_f32_16x16x32_bf16 v[66:69], v[172:175], v[208:211], v[66:69]
	s_setprio 0
	s_barrier
	s_add_i32 s38, s78, s49
	v_lshl_add_u64 v[212:213], v[212:213], 0, s[70:71]
	s_mov_b32 m0, s38
	ds_read_b128 v[180:183], v179 offset:49152
	ds_read_b128 v[184:187], v179 offset:50176
	ds_read_b128 v[188:191], v179 offset:51200
	ds_read_b128 v[192:195], v179 offset:52224
	ds_read_b128 v[196:199], v179 offset:53248
	ds_read_b128 v[200:203], v179 offset:54272
	ds_read_b128 v[204:207], v179 offset:55296
	ds_read_b128 v[208:211], v179 offset:56320
	global_load_lds_dwordx4 v[212:213], off
	s_add_i32 m0, s38, 0x2000
	s_add_u32 s26, s26, 0xb0080
	v_lshl_add_u64 v[212:213], v[214:215], 0, s[70:71]
	s_addc_u32 s27, s27, 0
	s_add_i32 s38, s79, s49
	global_load_lds_dwordx4 v[212:213], off
	v_lshl_add_u64 v[212:213], s[26:27], 0, v[0:1]
	s_mov_b32 m0, s38
	s_nop 0
	global_load_lds_dwordx4 v[212:213], off
	v_lshl_add_u64 v[212:213], s[26:27], 0, v[134:135]
	s_add_i32 m0, s38, 0x2000
	s_nop 0
	global_load_lds_dwordx4 v[212:213], off
	v_lshl_add_u64 v[212:213], v[216:217], 0, s[70:71]
	s_mov_b32 m0, s74
	s_nop 0
	global_load_lds_dwordx4 v[212:213], off
	v_lshl_add_u64 v[212:213], v[218:219], 0, s[70:71]
	s_mov_b32 m0, s75
	s_nop 0
	global_load_lds_dwordx4 v[212:213], off
	s_waitcnt vmcnt(8)
	s_waitcnt lgkmcnt(0)
	s_barrier
	s_setprio 1
	v_mfma_f32_16x16x32_bf16 v[62:65], v[140:143], v[180:183], v[62:65]
	v_mfma_f32_16x16x32_bf16 v[58:61], v[148:151], v[180:183], v[58:61]
	v_mfma_f32_16x16x32_bf16 v[46:49], v[140:143], v[188:191], v[46:49]
	v_mfma_f32_16x16x32_bf16 v[42:45], v[148:151], v[188:191], v[42:45]
	v_mfma_f32_16x16x32_bf16 v[30:33], v[140:143], v[196:199], v[30:33]
	v_mfma_f32_16x16x32_bf16 v[26:29], v[148:151], v[196:199], v[26:29]
	v_mfma_f32_16x16x32_bf16 v[14:17], v[140:143], v[204:207], v[14:17]
	v_mfma_f32_16x16x32_bf16 v[10:13], v[148:151], v[204:207], v[10:13]
	v_mfma_f32_16x16x32_bf16 v[62:65], v[144:147], v[184:187], v[62:65]
	v_mfma_f32_16x16x32_bf16 v[58:61], v[156:159], v[184:187], v[58:61]
	v_mfma_f32_16x16x32_bf16 v[46:49], v[144:147], v[192:195], v[46:49]
	v_mfma_f32_16x16x32_bf16 v[42:45], v[156:159], v[192:195], v[42:45]
	v_mfma_f32_16x16x32_bf16 v[30:33], v[144:147], v[200:203], v[30:33]
	v_mfma_f32_16x16x32_bf16 v[26:29], v[156:159], v[200:203], v[26:29]
	v_mfma_f32_16x16x32_bf16 v[14:17], v[144:147], v[208:211], v[14:17]
	v_mfma_f32_16x16x32_bf16 v[10:13], v[156:159], v[208:211], v[10:13]
	v_mfma_f32_16x16x32_bf16 v[54:57], v[160:163], v[180:183], v[54:57]
	v_mfma_f32_16x16x32_bf16 v[50:53], v[168:171], v[180:183], v[50:53]
	v_mfma_f32_16x16x32_bf16 v[38:41], v[160:163], v[188:191], v[38:41]
	v_mfma_f32_16x16x32_bf16 v[34:37], v[168:171], v[188:191], v[34:37]
	v_mfma_f32_16x16x32_bf16 v[22:25], v[160:163], v[196:199], v[22:25]
	v_mfma_f32_16x16x32_bf16 v[18:21], v[168:171], v[196:199], v[18:21]
	v_mfma_f32_16x16x32_bf16 v[6:9], v[160:163], v[204:207], v[6:9]
	v_mfma_f32_16x16x32_bf16 v[2:5], v[168:171], v[204:207], v[2:5]
	v_mfma_f32_16x16x32_bf16 v[54:57], v[164:167], v[184:187], v[54:57]
	v_mfma_f32_16x16x32_bf16 v[50:53], v[172:175], v[184:187], v[50:53]
	v_mfma_f32_16x16x32_bf16 v[38:41], v[164:167], v[192:195], v[38:41]
	v_mfma_f32_16x16x32_bf16 v[34:37], v[172:175], v[192:195], v[34:37]
	v_mfma_f32_16x16x32_bf16 v[22:25], v[164:167], v[200:203], v[22:25]
	v_mfma_f32_16x16x32_bf16 v[18:21], v[172:175], v[200:203], v[18:21]
	v_mfma_f32_16x16x32_bf16 v[6:9], v[164:167], v[208:211], v[6:9]
	v_mfma_f32_16x16x32_bf16 v[2:5], v[172:175], v[208:211], v[2:5]
	s_setprio 0
	s_barrier
	s_add_u32 vcc_lo, vcc_lo, 0x100
	s_addc_u32 vcc_hi, vcc_hi, 0
	s_cmp_ge_u32 s9, s28
	s_mov_b64 s[38:39], s[60:61]
	s_mov_b32 s26, s9
	s_cbranch_scc0 .LBB0_950
	s_and_b64 vcc, exec, s[22:23]
	s_cbranch_vccz .LBB0_953

.LBB0_1000:
	s_add_i32 s9, s26, 2
	s_add_u32 s60, s38, 0x100
	s_addc_u32 s61, s39, 0
	s_add_i32 s78, 0, 0x10000
	s_cmp_eq_u32 s29, s26
	s_cselect_b32 s73, s25, s61
	s_cselect_b32 s72, s24, s60
	v_add_u32_e32 v148, s78, v251
	s_cselect_b32 s27, s37, vcc_hi
	s_cselect_b32 s26, s36, vcc_lo
	s_add_i32 s79, 0, 0x14000
	ds_read_b128 v[140:143], v148
	ds_read_b128 v[144:147], v148 offset:1024
	ds_read_b128 v[156:159], v148 offset:2048
	ds_read_b128 v[160:163], v148 offset:3072
	v_add_u32_e32 v148, s79, v251
	ds_read_b128 v[164:167], v148
	ds_read_b128 v[168:171], v148 offset:1024
	ds_read_b128 v[172:175], v148 offset:2048
	ds_read_b128 v[176:179], v148 offset:3072
	v_lshl_add_u64 v[148:149], s[38:39], 0, v[136:137]
	s_add_i32 m0, s50, 0xc000
	ds_read_b128 v[180:183], v253
	ds_read_b128 v[184:187], v253 offset:1024
	ds_read_b128 v[188:191], v253 offset:2048
	ds_read_b128 v[192:195], v253 offset:3072
	ds_read_b128 v[196:199], v253 offset:4096
	ds_read_b128 v[200:203], v253 offset:5120
	ds_read_b128 v[204:207], v253 offset:6144
	ds_read_b128 v[208:211], v253 offset:7168
	global_load_lds_dwordx4 v[148:149], off
	v_lshl_add_u64 v[148:149], s[38:39], 0, v[138:139]
	s_add_i32 m0, s50, 0xe000
	s_nop 0
	global_load_lds_dwordx4 v[148:149], off
	s_waitcnt vmcnt(8)
	s_waitcnt lgkmcnt(0)
	s_barrier
	s_setprio 1
	v_mfma_f32_16x16x32_bf16 v[126:129], v[140:143], v[180:183], v[126:129]
	v_mfma_f32_16x16x32_bf16 v[122:125], v[156:159], v[180:183], v[122:125]
	v_mfma_f32_16x16x32_bf16 v[110:113], v[140:143], v[188:191], v[110:113]
	v_mfma_f32_16x16x32_bf16 v[106:109], v[156:159], v[188:191], v[106:109]
	v_mfma_f32_16x16x32_bf16 v[94:97], v[140:143], v[196:199], v[94:97]
	v_mfma_f32_16x16x32_bf16 v[90:93], v[156:159], v[196:199], v[90:93]
	v_mfma_f32_16x16x32_bf16 v[78:81], v[140:143], v[204:207], v[78:81]
	v_mfma_f32_16x16x32_bf16 v[74:77], v[156:159], v[204:207], v[74:77]
	v_mfma_f32_16x16x32_bf16 v[126:129], v[144:147], v[184:187], v[126:129]
	v_mfma_f32_16x16x32_bf16 v[122:125], v[160:163], v[184:187], v[122:125]
	v_mfma_f32_16x16x32_bf16 v[110:113], v[144:147], v[192:195], v[110:113]
	v_mfma_f32_16x16x32_bf16 v[106:109], v[160:163], v[192:195], v[106:109]
	v_mfma_f32_16x16x32_bf16 v[94:97], v[144:147], v[200:203], v[94:97]
	v_mfma_f32_16x16x32_bf16 v[90:93], v[160:163], v[200:203], v[90:93]
	v_mfma_f32_16x16x32_bf16 v[78:81], v[144:147], v[208:211], v[78:81]
	v_mfma_f32_16x16x32_bf16 v[74:77], v[160:163], v[208:211], v[74:77]
	v_mfma_f32_16x16x32_bf16 v[118:121], v[164:167], v[180:183], v[118:121]
	v_mfma_f32_16x16x32_bf16 v[114:117], v[172:175], v[180:183], v[114:117]
	v_mfma_f32_16x16x32_bf16 v[102:105], v[164:167], v[188:191], v[102:105]
	v_mfma_f32_16x16x32_bf16 v[98:101], v[172:175], v[188:191], v[98:101]
	v_mfma_f32_16x16x32_bf16 v[86:89], v[164:167], v[196:199], v[86:89]
	v_mfma_f32_16x16x32_bf16 v[82:85], v[172:175], v[196:199], v[82:85]
	v_mfma_f32_16x16x32_bf16 v[70:73], v[164:167], v[204:207], v[70:73]
	v_mfma_f32_16x16x32_bf16 v[66:69], v[172:175], v[204:207], v[66:69]
	v_mfma_f32_16x16x32_bf16 v[118:121], v[168:171], v[184:187], v[118:121]
	v_mfma_f32_16x16x32_bf16 v[114:117], v[176:179], v[184:187], v[114:117]
	v_mfma_f32_16x16x32_bf16 v[102:105], v[168:171], v[192:195], v[102:105]
	v_mfma_f32_16x16x32_bf16 v[98:101], v[176:179], v[192:195], v[98:101]
	v_mfma_f32_16x16x32_bf16 v[86:89], v[168:171], v[200:203], v[86:89]
	v_mfma_f32_16x16x32_bf16 v[82:85], v[176:179], v[200:203], v[82:85]
	v_mfma_f32_16x16x32_bf16 v[70:73], v[168:171], v[208:211], v[70:73]
	v_mfma_f32_16x16x32_bf16 v[66:69], v[176:179], v[208:211], v[66:69]
	s_setprio 0
	s_barrier
	s_add_i32 s38, s78, s49
	v_lshl_add_u64 v[148:149], s[26:27], 0, v[0:1]
	s_mov_b32 m0, s38
	ds_read_b128 v[180:183], v253 offset:16384
	ds_read_b128 v[184:187], v253 offset:17408
	ds_read_b128 v[188:191], v253 offset:18432
	ds_read_b128 v[192:195], v253 offset:19456
	ds_read_b128 v[196:199], v253 offset:20480
	ds_read_b128 v[200:203], v253 offset:21504
	ds_read_b128 v[204:207], v253 offset:22528
	ds_read_b128 v[208:211], v253 offset:23552
	global_load_lds_dwordx4 v[148:149], off
	s_add_i32 m0, s38, 0x2000
	s_add_u32 s38, s26, 0xb0000
	v_lshl_add_u64 v[150:151], s[26:27], 0, v[134:135]
	s_addc_u32 s39, s27, 0
	s_add_i32 s78, s79, s49
	global_load_lds_dwordx4 v[150:151], off
	v_lshl_add_u64 v[212:213], s[38:39], 0, v[0:1]
	s_mov_b32 m0, s78
	v_lshl_add_u64 v[214:215], s[72:73], 0, v[132:133]
	global_load_lds_dwordx4 v[212:213], off
	v_lshl_add_u64 v[212:213], s[38:39], 0, v[134:135]
	s_add_i32 m0, s78, 0x2000
	s_nop 0
	global_load_lds_dwordx4 v[212:213], off
	v_lshl_add_u64 v[212:213], s[72:73], 0, v[130:131]
	s_mov_b32 m0, s50
	s_nop 0
	global_load_lds_dwordx4 v[212:213], off
	s_mov_b32 m0, s51
	s_nop 0
	global_load_lds_dwordx4 v[214:215], off
	s_waitcnt vmcnt(8)
	s_waitcnt lgkmcnt(0)
	s_barrier
	s_setprio 1
	v_mfma_f32_16x16x32_bf16 v[62:65], v[140:143], v[180:183], v[62:65]
	v_mfma_f32_16x16x32_bf16 v[58:61], v[156:159], v[180:183], v[58:61]
	v_mfma_f32_16x16x32_bf16 v[46:49], v[140:143], v[188:191], v[46:49]
	v_mfma_f32_16x16x32_bf16 v[42:45], v[156:159], v[188:191], v[42:45]
	v_mfma_f32_16x16x32_bf16 v[30:33], v[140:143], v[196:199], v[30:33]
	v_mfma_f32_16x16x32_bf16 v[26:29], v[156:159], v[196:199], v[26:29]
	v_mfma_f32_16x16x32_bf16 v[14:17], v[140:143], v[204:207], v[14:17]
	v_mfma_f32_16x16x32_bf16 v[10:13], v[156:159], v[204:207], v[10:13]
	v_mfma_f32_16x16x32_bf16 v[62:65], v[144:147], v[184:187], v[62:65]
	v_mfma_f32_16x16x32_bf16 v[58:61], v[160:163], v[184:187], v[58:61]
	v_mfma_f32_16x16x32_bf16 v[46:49], v[144:147], v[192:195], v[46:49]
	v_mfma_f32_16x16x32_bf16 v[42:45], v[160:163], v[192:195], v[42:45]
	v_mfma_f32_16x16x32_bf16 v[30:33], v[144:147], v[200:203], v[30:33]
	v_mfma_f32_16x16x32_bf16 v[26:29], v[160:163], v[200:203], v[26:29]
	v_mfma_f32_16x16x32_bf16 v[14:17], v[144:147], v[208:211], v[14:17]
	v_mfma_f32_16x16x32_bf16 v[10:13], v[160:163], v[208:211], v[10:13]
	v_mfma_f32_16x16x32_bf16 v[54:57], v[164:167], v[180:183], v[54:57]
	v_mfma_f32_16x16x32_bf16 v[50:53], v[172:175], v[180:183], v[50:53]
	v_mfma_f32_16x16x32_bf16 v[38:41], v[164:167], v[188:191], v[38:41]
	v_mfma_f32_16x16x32_bf16 v[34:37], v[172:175], v[188:191], v[34:37]
	v_mfma_f32_16x16x32_bf16 v[22:25], v[164:167], v[196:199], v[22:25]
	v_mfma_f32_16x16x32_bf16 v[18:21], v[172:175], v[196:199], v[18:21]
	v_mfma_f32_16x16x32_bf16 v[6:9], v[164:167], v[204:207], v[6:9]
	v_mfma_f32_16x16x32_bf16 v[2:5], v[172:175], v[204:207], v[2:5]
	v_mfma_f32_16x16x32_bf16 v[54:57], v[168:171], v[184:187], v[54:57]
	v_mfma_f32_16x16x32_bf16 v[50:53], v[176:179], v[184:187], v[50:53]
	v_mfma_f32_16x16x32_bf16 v[38:41], v[168:171], v[192:195], v[38:41]
	v_mfma_f32_16x16x32_bf16 v[34:37], v[176:179], v[192:195], v[34:37]
	v_mfma_f32_16x16x32_bf16 v[22:25], v[168:171], v[200:203], v[22:25]
	v_mfma_f32_16x16x32_bf16 v[18:21], v[176:179], v[200:203], v[18:21]
	v_mfma_f32_16x16x32_bf16 v[6:9], v[168:171], v[208:211], v[6:9]
	v_mfma_f32_16x16x32_bf16 v[2:5], v[176:179], v[208:211], v[2:5]
	s_setprio 0
	s_barrier
	s_add_i32 s78, 0, 0x18000
	s_add_i32 s79, 0, 0x1c000
	v_add_u32_e32 v160, s78, v251
	v_add_u32_e32 v176, s79, v251
	ds_read_b128 v[140:143], v160
	ds_read_b128 v[144:147], v160 offset:1024
	ds_read_b128 v[156:159], v160 offset:2048
	ds_read_b128 v[160:163], v160 offset:3072
	ds_read_b128 v[164:167], v176
	ds_read_b128 v[168:171], v176 offset:1024
	ds_read_b128 v[172:175], v176 offset:2048
	ds_read_b128 v[176:179], v176 offset:3072
	s_add_u32 s38, s72, 0xb0000
	s_addc_u32 s39, s73, 0
	s_mov_b32 m0, s52
	v_lshl_add_u64 v[216:217], s[38:39], 0, v[130:131]
	ds_read_b128 v[180:183], v253 offset:32768
	ds_read_b128 v[184:187], v253 offset:33792
	ds_read_b128 v[188:191], v253 offset:34816
	ds_read_b128 v[192:195], v253 offset:35840
	ds_read_b128 v[196:199], v253 offset:36864
	ds_read_b128 v[200:203], v253 offset:37888
	ds_read_b128 v[204:207], v253 offset:38912
	ds_read_b128 v[208:211], v253 offset:39936
	global_load_lds_dwordx4 v[216:217], off
	v_lshl_add_u64 v[216:217], s[38:39], 0, v[132:133]
	s_mov_b32 m0, s53
	s_nop 0
	global_load_lds_dwordx4 v[216:217], off
	s_waitcnt vmcnt(8)
	s_waitcnt lgkmcnt(0)
	s_barrier
	s_setprio 1
	v_mfma_f32_16x16x32_bf16 v[126:129], v[140:143], v[180:183], v[126:129]
	v_mfma_f32_16x16x32_bf16 v[122:125], v[156:159], v[180:183], v[122:125]
	v_mfma_f32_16x16x32_bf16 v[110:113], v[140:143], v[188:191], v[110:113]
	v_mfma_f32_16x16x32_bf16 v[106:109], v[156:159], v[188:191], v[106:109]
	v_mfma_f32_16x16x32_bf16 v[94:97], v[140:143], v[196:199], v[94:97]
	v_mfma_f32_16x16x32_bf16 v[90:93], v[156:159], v[196:199], v[90:93]
	v_mfma_f32_16x16x32_bf16 v[78:81], v[140:143], v[204:207], v[78:81]
	v_mfma_f32_16x16x32_bf16 v[74:77], v[156:159], v[204:207], v[74:77]
	v_mfma_f32_16x16x32_bf16 v[126:129], v[144:147], v[184:187], v[126:129]
	v_mfma_f32_16x16x32_bf16 v[122:125], v[160:163], v[184:187], v[122:125]
	v_mfma_f32_16x16x32_bf16 v[110:113], v[144:147], v[192:195], v[110:113]
	v_mfma_f32_16x16x32_bf16 v[106:109], v[160:163], v[192:195], v[106:109]
	v_mfma_f32_16x16x32_bf16 v[94:97], v[144:147], v[200:203], v[94:97]
	v_mfma_f32_16x16x32_bf16 v[90:93], v[160:163], v[200:203], v[90:93]
	v_mfma_f32_16x16x32_bf16 v[78:81], v[144:147], v[208:211], v[78:81]
	v_mfma_f32_16x16x32_bf16 v[74:77], v[160:163], v[208:211], v[74:77]
	v_mfma_f32_16x16x32_bf16 v[118:121], v[164:167], v[180:183], v[118:121]
	v_mfma_f32_16x16x32_bf16 v[114:117], v[172:175], v[180:183], v[114:117]
	v_mfma_f32_16x16x32_bf16 v[102:105], v[164:167], v[188:191], v[102:105]
	v_mfma_f32_16x16x32_bf16 v[98:101], v[172:175], v[188:191], v[98:101]
	v_mfma_f32_16x16x32_bf16 v[86:89], v[164:167], v[196:199], v[86:89]
	v_mfma_f32_16x16x32_bf16 v[82:85], v[172:175], v[196:199], v[82:85]
	v_mfma_f32_16x16x32_bf16 v[70:73], v[164:167], v[204:207], v[70:73]
	v_mfma_f32_16x16x32_bf16 v[66:69], v[172:175], v[204:207], v[66:69]
	v_mfma_f32_16x16x32_bf16 v[118:121], v[168:171], v[184:187], v[118:121]
	v_mfma_f32_16x16x32_bf16 v[114:117], v[176:179], v[184:187], v[114:117]
	v_mfma_f32_16x16x32_bf16 v[102:105], v[168:171], v[192:195], v[102:105]
	v_mfma_f32_16x16x32_bf16 v[98:101], v[176:179], v[192:195], v[98:101]
	v_mfma_f32_16x16x32_bf16 v[86:89], v[168:171], v[200:203], v[86:89]
	v_mfma_f32_16x16x32_bf16 v[82:85], v[176:179], v[200:203], v[82:85]
	v_mfma_f32_16x16x32_bf16 v[70:73], v[168:171], v[208:211], v[70:73]
	v_mfma_f32_16x16x32_bf16 v[66:69], v[176:179], v[208:211], v[66:69]
	s_setprio 0
	s_barrier
	s_add_i32 s38, s78, s49
	v_lshl_add_u64 v[148:149], v[148:149], 0, s[70:71]
	s_mov_b32 m0, s38
	ds_read_b128 v[180:183], v253 offset:49152
	ds_read_b128 v[184:187], v253 offset:50176
	ds_read_b128 v[188:191], v253 offset:51200
	ds_read_b128 v[192:195], v253 offset:52224
	ds_read_b128 v[196:199], v253 offset:53248
	ds_read_b128 v[200:203], v253 offset:54272
	ds_read_b128 v[204:207], v253 offset:55296
	ds_read_b128 v[208:211], v253 offset:56320
	global_load_lds_dwordx4 v[148:149], off
	s_add_i32 m0, s38, 0x2000
	s_add_u32 s26, s26, 0xb0080
	v_lshl_add_u64 v[148:149], v[150:151], 0, s[70:71]
	s_addc_u32 s27, s27, 0
	s_add_i32 s38, s79, s49
	global_load_lds_dwordx4 v[148:149], off
	v_lshl_add_u64 v[148:149], s[26:27], 0, v[0:1]
	s_mov_b32 m0, s38
	s_nop 0
	global_load_lds_dwordx4 v[148:149], off
	v_lshl_add_u64 v[148:149], s[26:27], 0, v[134:135]
	s_add_i32 m0, s38, 0x2000
	s_nop 0
	global_load_lds_dwordx4 v[148:149], off
	v_lshl_add_u64 v[148:149], v[212:213], 0, s[70:71]
	s_mov_b32 m0, s74
	s_nop 0
	global_load_lds_dwordx4 v[148:149], off
	v_lshl_add_u64 v[148:149], v[214:215], 0, s[70:71]
	s_mov_b32 m0, s75
	s_nop 0
	global_load_lds_dwordx4 v[148:149], off
	s_waitcnt vmcnt(8)
	s_waitcnt lgkmcnt(0)
	s_barrier
	s_setprio 1
	v_mfma_f32_16x16x32_bf16 v[62:65], v[140:143], v[180:183], v[62:65]
	v_mfma_f32_16x16x32_bf16 v[58:61], v[156:159], v[180:183], v[58:61]
	v_mfma_f32_16x16x32_bf16 v[46:49], v[140:143], v[188:191], v[46:49]
	v_mfma_f32_16x16x32_bf16 v[42:45], v[156:159], v[188:191], v[42:45]
	v_mfma_f32_16x16x32_bf16 v[30:33], v[140:143], v[196:199], v[30:33]
	v_mfma_f32_16x16x32_bf16 v[26:29], v[156:159], v[196:199], v[26:29]
	v_mfma_f32_16x16x32_bf16 v[14:17], v[140:143], v[204:207], v[14:17]
	v_mfma_f32_16x16x32_bf16 v[10:13], v[156:159], v[204:207], v[10:13]
	v_mfma_f32_16x16x32_bf16 v[62:65], v[144:147], v[184:187], v[62:65]
	v_mfma_f32_16x16x32_bf16 v[58:61], v[160:163], v[184:187], v[58:61]
	v_mfma_f32_16x16x32_bf16 v[46:49], v[144:147], v[192:195], v[46:49]
	v_mfma_f32_16x16x32_bf16 v[42:45], v[160:163], v[192:195], v[42:45]
	v_mfma_f32_16x16x32_bf16 v[30:33], v[144:147], v[200:203], v[30:33]
	v_mfma_f32_16x16x32_bf16 v[26:29], v[160:163], v[200:203], v[26:29]
	v_mfma_f32_16x16x32_bf16 v[14:17], v[144:147], v[208:211], v[14:17]
	v_mfma_f32_16x16x32_bf16 v[10:13], v[160:163], v[208:211], v[10:13]
	v_mfma_f32_16x16x32_bf16 v[54:57], v[164:167], v[180:183], v[54:57]
	v_mfma_f32_16x16x32_bf16 v[50:53], v[172:175], v[180:183], v[50:53]
	v_mfma_f32_16x16x32_bf16 v[38:41], v[164:167], v[188:191], v[38:41]
	v_mfma_f32_16x16x32_bf16 v[34:37], v[172:175], v[188:191], v[34:37]
	v_mfma_f32_16x16x32_bf16 v[22:25], v[164:167], v[196:199], v[22:25]
	v_mfma_f32_16x16x32_bf16 v[18:21], v[172:175], v[196:199], v[18:21]
	v_mfma_f32_16x16x32_bf16 v[6:9], v[164:167], v[204:207], v[6:9]
	v_mfma_f32_16x16x32_bf16 v[2:5], v[172:175], v[204:207], v[2:5]
	v_mfma_f32_16x16x32_bf16 v[54:57], v[168:171], v[184:187], v[54:57]
	v_mfma_f32_16x16x32_bf16 v[50:53], v[176:179], v[184:187], v[50:53]
	v_mfma_f32_16x16x32_bf16 v[38:41], v[168:171], v[192:195], v[38:41]
	v_mfma_f32_16x16x32_bf16 v[34:37], v[176:179], v[192:195], v[34:37]
	v_mfma_f32_16x16x32_bf16 v[22:25], v[168:171], v[200:203], v[22:25]
	v_mfma_f32_16x16x32_bf16 v[18:21], v[176:179], v[200:203], v[18:21]
	v_mfma_f32_16x16x32_bf16 v[6:9], v[168:171], v[208:211], v[6:9]
	v_mfma_f32_16x16x32_bf16 v[2:5], v[176:179], v[208:211], v[2:5]
	s_setprio 0
	s_barrier
	s_add_u32 vcc_lo, vcc_lo, 0x100
	s_addc_u32 vcc_hi, vcc_hi, 0
	s_cmp_ge_u32 s9, s28
	s_mov_b64 s[38:39], s[60:61]
	s_mov_b32 s26, s9
	s_cbranch_scc0 .LBB0_1000
	s_and_b64 vcc, exec, s[22:23]
	s_cbranch_vccz .LBB0_1003

.LBB0_1054:
	s_add_i32 s96, s26, 2
	s_add_u32 s36, s24, 0x100
	s_addc_u32 s37, s25, 0
	s_add_i32 s9, 0, 0x10000
	s_cmp_eq_u32 s93, s26
	s_cselect_b32 s39, s15, s37
	s_cselect_b32 s38, s14, s36
	v_add_u32_e32 v148, s9, v177
	s_cselect_b32 s27, s23, s95
	s_cselect_b32 s26, s22, s94
	s_add_i32 s78, 0, 0x14000
	ds_read_b128 v[140:143], v148
	ds_read_b128 v[144:147], v148 offset:1024
	ds_read_b128 v[156:159], v148 offset:2048
	ds_read_b128 v[160:163], v148 offset:3072
	v_add_u32_e32 v148, s78, v177
	ds_read_b128 v[164:167], v148
	ds_read_b128 v[168:171], v148 offset:1024
	ds_read_b128 v[172:175], v148 offset:2048
	ds_read_b128 v[180:183], v148 offset:3072
	v_lshl_add_u64 v[148:149], s[24:25], 0, v[136:137]
	s_add_i32 m0, s29, 0xc000
	ds_read_b128 v[184:187], v179
	ds_read_b128 v[188:191], v179 offset:1024
	ds_read_b128 v[192:195], v179 offset:2048
	ds_read_b128 v[196:199], v179 offset:3072
	ds_read_b128 v[200:203], v179 offset:4096
	ds_read_b128 v[204:207], v179 offset:5120
	ds_read_b128 v[208:211], v179 offset:6144
	ds_read_b128 v[212:215], v179 offset:7168
	global_load_lds_dwordx4 v[148:149], off
	v_lshl_add_u64 v[148:149], s[24:25], 0, v[138:139]
	s_add_i32 m0, s29, 0xe000
	s_nop 0
	global_load_lds_dwordx4 v[148:149], off
	s_waitcnt vmcnt(8)
	s_waitcnt lgkmcnt(0)
	s_barrier
	s_setprio 1
	v_mfma_f32_16x16x32_bf16 v[126:129], v[140:143], v[184:187], v[126:129]
	v_mfma_f32_16x16x32_bf16 v[122:125], v[156:159], v[184:187], v[122:125]
	v_mfma_f32_16x16x32_bf16 v[110:113], v[140:143], v[192:195], v[110:113]
	v_mfma_f32_16x16x32_bf16 v[106:109], v[156:159], v[192:195], v[106:109]
	v_mfma_f32_16x16x32_bf16 v[94:97], v[140:143], v[200:203], v[94:97]
	v_mfma_f32_16x16x32_bf16 v[90:93], v[156:159], v[200:203], v[90:93]
	v_mfma_f32_16x16x32_bf16 v[78:81], v[140:143], v[208:211], v[78:81]
	v_mfma_f32_16x16x32_bf16 v[74:77], v[156:159], v[208:211], v[74:77]
	v_mfma_f32_16x16x32_bf16 v[126:129], v[144:147], v[188:191], v[126:129]
	v_mfma_f32_16x16x32_bf16 v[122:125], v[160:163], v[188:191], v[122:125]
	v_mfma_f32_16x16x32_bf16 v[110:113], v[144:147], v[196:199], v[110:113]
	v_mfma_f32_16x16x32_bf16 v[106:109], v[160:163], v[196:199], v[106:109]
	v_mfma_f32_16x16x32_bf16 v[94:97], v[144:147], v[204:207], v[94:97]
	v_mfma_f32_16x16x32_bf16 v[90:93], v[160:163], v[204:207], v[90:93]
	v_mfma_f32_16x16x32_bf16 v[78:81], v[144:147], v[212:215], v[78:81]
	v_mfma_f32_16x16x32_bf16 v[74:77], v[160:163], v[212:215], v[74:77]
	v_mfma_f32_16x16x32_bf16 v[118:121], v[164:167], v[184:187], v[118:121]
	v_mfma_f32_16x16x32_bf16 v[114:117], v[172:175], v[184:187], v[114:117]
	v_mfma_f32_16x16x32_bf16 v[102:105], v[164:167], v[192:195], v[102:105]
	v_mfma_f32_16x16x32_bf16 v[98:101], v[172:175], v[192:195], v[98:101]
	v_mfma_f32_16x16x32_bf16 v[86:89], v[164:167], v[200:203], v[86:89]
	v_mfma_f32_16x16x32_bf16 v[82:85], v[172:175], v[200:203], v[82:85]
	v_mfma_f32_16x16x32_bf16 v[70:73], v[164:167], v[208:211], v[70:73]
	v_mfma_f32_16x16x32_bf16 v[66:69], v[172:175], v[208:211], v[66:69]
	v_mfma_f32_16x16x32_bf16 v[118:121], v[168:171], v[188:191], v[118:121]
	v_mfma_f32_16x16x32_bf16 v[114:117], v[180:183], v[188:191], v[114:117]
	v_mfma_f32_16x16x32_bf16 v[102:105], v[168:171], v[196:199], v[102:105]
	v_mfma_f32_16x16x32_bf16 v[98:101], v[180:183], v[196:199], v[98:101]
	v_mfma_f32_16x16x32_bf16 v[86:89], v[168:171], v[204:207], v[86:89]
	v_mfma_f32_16x16x32_bf16 v[82:85], v[180:183], v[204:207], v[82:85]
	v_mfma_f32_16x16x32_bf16 v[70:73], v[168:171], v[212:215], v[70:73]
	v_mfma_f32_16x16x32_bf16 v[66:69], v[180:183], v[212:215], v[66:69]
	s_setprio 0
	s_barrier
	s_add_i32 s9, s9, s28
	v_lshl_add_u64 v[148:149], s[26:27], 0, v[0:1]
	s_mov_b32 m0, s9
	ds_read_b128 v[184:187], v179 offset:16384
	ds_read_b128 v[188:191], v179 offset:17408
	ds_read_b128 v[192:195], v179 offset:18432
	ds_read_b128 v[196:199], v179 offset:19456
	ds_read_b128 v[200:203], v179 offset:20480
	ds_read_b128 v[204:207], v179 offset:21504
	ds_read_b128 v[208:211], v179 offset:22528
	ds_read_b128 v[212:215], v179 offset:23552
	global_load_lds_dwordx4 v[148:149], off
	s_add_i32 m0, s9, 0x2000
	s_add_u32 s24, s26, 0xb0000
	v_lshl_add_u64 v[150:151], s[26:27], 0, v[134:135]
	s_addc_u32 s25, s27, 0
	s_add_i32 s9, s78, s28
	global_load_lds_dwordx4 v[150:151], off
	v_lshl_add_u64 v[216:217], s[24:25], 0, v[0:1]
	s_mov_b32 m0, s9
	v_lshl_add_u64 v[218:219], s[38:39], 0, v[132:133]
	global_load_lds_dwordx4 v[216:217], off
	v_lshl_add_u64 v[216:217], s[24:25], 0, v[134:135]
	s_add_i32 m0, s9, 0x2000
	s_nop 0
	global_load_lds_dwordx4 v[216:217], off
	v_lshl_add_u64 v[216:217], s[38:39], 0, v[130:131]
	s_mov_b32 m0, s29
	s_nop 0
	global_load_lds_dwordx4 v[216:217], off
	s_mov_b32 m0, s49
	s_nop 0
	global_load_lds_dwordx4 v[218:219], off
	s_waitcnt vmcnt(8)
	s_waitcnt lgkmcnt(0)
	s_barrier
	s_setprio 1
	v_mfma_f32_16x16x32_bf16 v[62:65], v[140:143], v[184:187], v[62:65]
	v_mfma_f32_16x16x32_bf16 v[58:61], v[156:159], v[184:187], v[58:61]
	v_mfma_f32_16x16x32_bf16 v[46:49], v[140:143], v[192:195], v[46:49]
	v_mfma_f32_16x16x32_bf16 v[42:45], v[156:159], v[192:195], v[42:45]
	v_mfma_f32_16x16x32_bf16 v[30:33], v[140:143], v[200:203], v[30:33]
	v_mfma_f32_16x16x32_bf16 v[26:29], v[156:159], v[200:203], v[26:29]
	v_mfma_f32_16x16x32_bf16 v[14:17], v[140:143], v[208:211], v[14:17]
	v_mfma_f32_16x16x32_bf16 v[10:13], v[156:159], v[208:211], v[10:13]
	v_mfma_f32_16x16x32_bf16 v[62:65], v[144:147], v[188:191], v[62:65]
	v_mfma_f32_16x16x32_bf16 v[58:61], v[160:163], v[188:191], v[58:61]
	v_mfma_f32_16x16x32_bf16 v[46:49], v[144:147], v[196:199], v[46:49]
	v_mfma_f32_16x16x32_bf16 v[42:45], v[160:163], v[196:199], v[42:45]
	v_mfma_f32_16x16x32_bf16 v[30:33], v[144:147], v[204:207], v[30:33]
	v_mfma_f32_16x16x32_bf16 v[26:29], v[160:163], v[204:207], v[26:29]
	v_mfma_f32_16x16x32_bf16 v[14:17], v[144:147], v[212:215], v[14:17]
	v_mfma_f32_16x16x32_bf16 v[10:13], v[160:163], v[212:215], v[10:13]
	v_mfma_f32_16x16x32_bf16 v[54:57], v[164:167], v[184:187], v[54:57]
	v_mfma_f32_16x16x32_bf16 v[50:53], v[172:175], v[184:187], v[50:53]
	v_mfma_f32_16x16x32_bf16 v[38:41], v[164:167], v[192:195], v[38:41]
	v_mfma_f32_16x16x32_bf16 v[34:37], v[172:175], v[192:195], v[34:37]
	v_mfma_f32_16x16x32_bf16 v[22:25], v[164:167], v[200:203], v[22:25]
	v_mfma_f32_16x16x32_bf16 v[18:21], v[172:175], v[200:203], v[18:21]
	v_mfma_f32_16x16x32_bf16 v[6:9], v[164:167], v[208:211], v[6:9]
	v_mfma_f32_16x16x32_bf16 v[2:5], v[172:175], v[208:211], v[2:5]
	v_mfma_f32_16x16x32_bf16 v[54:57], v[168:171], v[188:191], v[54:57]
	v_mfma_f32_16x16x32_bf16 v[50:53], v[180:183], v[188:191], v[50:53]
	v_mfma_f32_16x16x32_bf16 v[38:41], v[168:171], v[196:199], v[38:41]
	v_mfma_f32_16x16x32_bf16 v[34:37], v[180:183], v[196:199], v[34:37]
	v_mfma_f32_16x16x32_bf16 v[22:25], v[168:171], v[204:207], v[22:25]
	v_mfma_f32_16x16x32_bf16 v[18:21], v[180:183], v[204:207], v[18:21]
	v_mfma_f32_16x16x32_bf16 v[6:9], v[168:171], v[212:215], v[6:9]
	v_mfma_f32_16x16x32_bf16 v[2:5], v[180:183], v[212:215], v[2:5]
	s_setprio 0
	s_barrier
	s_add_i32 s9, 0, 0x18000
	s_add_i32 s78, 0, 0x1c000
	v_add_u32_e32 v160, s9, v177
	v_add_u32_e32 v180, s78, v177
	ds_read_b128 v[140:143], v160
	ds_read_b128 v[144:147], v160 offset:1024
	ds_read_b128 v[156:159], v160 offset:2048
	ds_read_b128 v[160:163], v160 offset:3072
	ds_read_b128 v[164:167], v180
	ds_read_b128 v[168:171], v180 offset:1024
	ds_read_b128 v[172:175], v180 offset:2048
	ds_read_b128 v[180:183], v180 offset:3072
	s_add_u32 s24, s38, 0xb0000
	s_addc_u32 s25, s39, 0
	s_mov_b32 m0, s50
	v_lshl_add_u64 v[220:221], s[24:25], 0, v[130:131]
	ds_read_b128 v[184:187], v179 offset:32768
	ds_read_b128 v[188:191], v179 offset:33792
	ds_read_b128 v[192:195], v179 offset:34816
	ds_read_b128 v[196:199], v179 offset:35840
	ds_read_b128 v[200:203], v179 offset:36864
	ds_read_b128 v[204:207], v179 offset:37888
	ds_read_b128 v[208:211], v179 offset:38912
	ds_read_b128 v[212:215], v179 offset:39936
	global_load_lds_dwordx4 v[220:221], off
	v_lshl_add_u64 v[220:221], s[24:25], 0, v[132:133]
	s_mov_b32 m0, s51
	s_nop 0
	global_load_lds_dwordx4 v[220:221], off
	s_waitcnt vmcnt(8)
	s_waitcnt lgkmcnt(0)
	s_barrier
	s_setprio 1
	v_mfma_f32_16x16x32_bf16 v[126:129], v[140:143], v[184:187], v[126:129]
	v_mfma_f32_16x16x32_bf16 v[122:125], v[156:159], v[184:187], v[122:125]
	v_mfma_f32_16x16x32_bf16 v[110:113], v[140:143], v[192:195], v[110:113]
	v_mfma_f32_16x16x32_bf16 v[106:109], v[156:159], v[192:195], v[106:109]
	v_mfma_f32_16x16x32_bf16 v[94:97], v[140:143], v[200:203], v[94:97]
	v_mfma_f32_16x16x32_bf16 v[90:93], v[156:159], v[200:203], v[90:93]
	v_mfma_f32_16x16x32_bf16 v[78:81], v[140:143], v[208:211], v[78:81]
	v_mfma_f32_16x16x32_bf16 v[74:77], v[156:159], v[208:211], v[74:77]
	v_mfma_f32_16x16x32_bf16 v[126:129], v[144:147], v[188:191], v[126:129]
	v_mfma_f32_16x16x32_bf16 v[122:125], v[160:163], v[188:191], v[122:125]
	v_mfma_f32_16x16x32_bf16 v[110:113], v[144:147], v[196:199], v[110:113]
	v_mfma_f32_16x16x32_bf16 v[106:109], v[160:163], v[196:199], v[106:109]
	v_mfma_f32_16x16x32_bf16 v[94:97], v[144:147], v[204:207], v[94:97]
	v_mfma_f32_16x16x32_bf16 v[90:93], v[160:163], v[204:207], v[90:93]
	v_mfma_f32_16x16x32_bf16 v[78:81], v[144:147], v[212:215], v[78:81]
	v_mfma_f32_16x16x32_bf16 v[74:77], v[160:163], v[212:215], v[74:77]
	v_mfma_f32_16x16x32_bf16 v[118:121], v[164:167], v[184:187], v[118:121]
	v_mfma_f32_16x16x32_bf16 v[114:117], v[172:175], v[184:187], v[114:117]
	v_mfma_f32_16x16x32_bf16 v[102:105], v[164:167], v[192:195], v[102:105]
	v_mfma_f32_16x16x32_bf16 v[98:101], v[172:175], v[192:195], v[98:101]
	v_mfma_f32_16x16x32_bf16 v[86:89], v[164:167], v[200:203], v[86:89]
	v_mfma_f32_16x16x32_bf16 v[82:85], v[172:175], v[200:203], v[82:85]
	v_mfma_f32_16x16x32_bf16 v[70:73], v[164:167], v[208:211], v[70:73]
	v_mfma_f32_16x16x32_bf16 v[66:69], v[172:175], v[208:211], v[66:69]
	v_mfma_f32_16x16x32_bf16 v[118:121], v[168:171], v[188:191], v[118:121]
	v_mfma_f32_16x16x32_bf16 v[114:117], v[180:183], v[188:191], v[114:117]
	v_mfma_f32_16x16x32_bf16 v[102:105], v[168:171], v[196:199], v[102:105]
	v_mfma_f32_16x16x32_bf16 v[98:101], v[180:183], v[196:199], v[98:101]
	v_mfma_f32_16x16x32_bf16 v[86:89], v[168:171], v[204:207], v[86:89]
	v_mfma_f32_16x16x32_bf16 v[82:85], v[180:183], v[204:207], v[82:85]
	v_mfma_f32_16x16x32_bf16 v[70:73], v[168:171], v[212:215], v[70:73]
	v_mfma_f32_16x16x32_bf16 v[66:69], v[180:183], v[212:215], v[66:69]
	s_setprio 0
	s_barrier
	s_add_i32 s9, s9, s28
	v_lshl_add_u64 v[148:149], v[148:149], 0, s[70:71]
	s_mov_b32 m0, s9
	ds_read_b128 v[184:187], v179 offset:49152
	ds_read_b128 v[188:191], v179 offset:50176
	ds_read_b128 v[192:195], v179 offset:51200
	ds_read_b128 v[196:199], v179 offset:52224
	ds_read_b128 v[200:203], v179 offset:53248
	ds_read_b128 v[204:207], v179 offset:54272
	ds_read_b128 v[208:211], v179 offset:55296
	ds_read_b128 v[212:215], v179 offset:56320
	global_load_lds_dwordx4 v[148:149], off
	s_add_i32 m0, s9, 0x2000
	s_add_u32 s24, s26, 0xb0080
	v_lshl_add_u64 v[148:149], v[150:151], 0, s[70:71]
	s_addc_u32 s25, s27, 0
	s_add_i32 s9, s78, s28
	global_load_lds_dwordx4 v[148:149], off
	v_lshl_add_u64 v[148:149], s[24:25], 0, v[0:1]
	s_mov_b32 m0, s9
	s_nop 0
	global_load_lds_dwordx4 v[148:149], off
	v_lshl_add_u64 v[148:149], s[24:25], 0, v[134:135]
	s_add_i32 m0, s9, 0x2000
	s_nop 0
	global_load_lds_dwordx4 v[148:149], off
	v_lshl_add_u64 v[148:149], v[216:217], 0, s[70:71]
	s_mov_b32 m0, s52
	s_nop 0
	global_load_lds_dwordx4 v[148:149], off
	v_lshl_add_u64 v[148:149], v[218:219], 0, s[70:71]
	s_mov_b32 m0, s53
	s_nop 0
	global_load_lds_dwordx4 v[148:149], off
	s_waitcnt vmcnt(8)
	s_waitcnt lgkmcnt(0)
	s_barrier
	s_setprio 1
	v_mfma_f32_16x16x32_bf16 v[62:65], v[140:143], v[184:187], v[62:65]
	v_mfma_f32_16x16x32_bf16 v[58:61], v[156:159], v[184:187], v[58:61]
	v_mfma_f32_16x16x32_bf16 v[46:49], v[140:143], v[192:195], v[46:49]
	v_mfma_f32_16x16x32_bf16 v[42:45], v[156:159], v[192:195], v[42:45]
	v_mfma_f32_16x16x32_bf16 v[30:33], v[140:143], v[200:203], v[30:33]
	v_mfma_f32_16x16x32_bf16 v[26:29], v[156:159], v[200:203], v[26:29]
	v_mfma_f32_16x16x32_bf16 v[14:17], v[140:143], v[208:211], v[14:17]
	v_mfma_f32_16x16x32_bf16 v[10:13], v[156:159], v[208:211], v[10:13]
	v_mfma_f32_16x16x32_bf16 v[62:65], v[144:147], v[188:191], v[62:65]
	v_mfma_f32_16x16x32_bf16 v[58:61], v[160:163], v[188:191], v[58:61]
	v_mfma_f32_16x16x32_bf16 v[46:49], v[144:147], v[196:199], v[46:49]
	v_mfma_f32_16x16x32_bf16 v[42:45], v[160:163], v[196:199], v[42:45]
	v_mfma_f32_16x16x32_bf16 v[30:33], v[144:147], v[204:207], v[30:33]
	v_mfma_f32_16x16x32_bf16 v[26:29], v[160:163], v[204:207], v[26:29]
	v_mfma_f32_16x16x32_bf16 v[14:17], v[144:147], v[212:215], v[14:17]
	v_mfma_f32_16x16x32_bf16 v[10:13], v[160:163], v[212:215], v[10:13]
	v_mfma_f32_16x16x32_bf16 v[54:57], v[164:167], v[184:187], v[54:57]
	v_mfma_f32_16x16x32_bf16 v[50:53], v[172:175], v[184:187], v[50:53]
	v_mfma_f32_16x16x32_bf16 v[38:41], v[164:167], v[192:195], v[38:41]
	v_mfma_f32_16x16x32_bf16 v[34:37], v[172:175], v[192:195], v[34:37]
	v_mfma_f32_16x16x32_bf16 v[22:25], v[164:167], v[200:203], v[22:25]
	v_mfma_f32_16x16x32_bf16 v[18:21], v[172:175], v[200:203], v[18:21]
	v_mfma_f32_16x16x32_bf16 v[6:9], v[164:167], v[208:211], v[6:9]
	v_mfma_f32_16x16x32_bf16 v[2:5], v[172:175], v[208:211], v[2:5]
	v_mfma_f32_16x16x32_bf16 v[54:57], v[168:171], v[188:191], v[54:57]
	v_mfma_f32_16x16x32_bf16 v[50:53], v[180:183], v[188:191], v[50:53]
	v_mfma_f32_16x16x32_bf16 v[38:41], v[168:171], v[196:199], v[38:41]
	v_mfma_f32_16x16x32_bf16 v[34:37], v[180:183], v[196:199], v[34:37]
	v_mfma_f32_16x16x32_bf16 v[22:25], v[168:171], v[204:207], v[22:25]
	v_mfma_f32_16x16x32_bf16 v[18:21], v[180:183], v[204:207], v[18:21]
	v_mfma_f32_16x16x32_bf16 v[6:9], v[168:171], v[212:215], v[6:9]
	v_mfma_f32_16x16x32_bf16 v[2:5], v[180:183], v[212:215], v[2:5]
	s_setprio 0
	s_barrier
	s_add_u32 s94, s94, 0x100
	s_addc_u32 s95, s95, 0
	s_cmp_ge_u32 s96, s92
	s_mov_b64 s[24:25], s[36:37]
	s_mov_b32 s26, s96
	s_cbranch_scc0 .LBB0_1054
	s_and_b64 vcc, exec, s[12:13]
	s_cbranch_vccz .LBB0_1057
